# nt cache policy on the read-once f32 weight loads of the bf16 transposes (on top of attention cleanups)
# baseline (speedup 1.0000x reference)
;     __device__ __forceinline__ const float* in(int i) const { return (const float*)(const __attribute__((address_space(1))) float*)ld(i); }
; __device__ __forceinline__ void phase_mod_partial(const DArgs& a, LAS unsigned char* lds) {
;     ...
;     for (int i = threadIdx.x; i < 9 * D; i += NTHR) { const int e = i / D, d = i % D; const float c = e == 0 ? a.in(I_CP)[d] : a.in(I_CS)[(e - 1) * D + d]; sil[i] = c / (1.f + __expf(-c)); }
.LBB0_21:
	s_or_b64 exec, exec, s[8:9]
	v_lshl_add_u64 v[2:3], v[0:1], 2, v[2:3]
	global_load_dword v0, v[2:3], off nt
	v_add_u32_e32 v3, 0x200, v6
	v_cmp_lt_u32_e32 vcc, s16, v6
	s_or_b64 s[0:1], vcc, s[0:1]
	s_waitcnt vmcnt(0)
	v_mul_f32_e32 v2, 0xbfb8aa3b, v0
	v_exp_f32_e32 v2, v2
	s_nop 0
	v_add_f32_e32 v2, 1.0, v2
	v_div_scale_f32 v6, s[4:5], v2, v2, v0
	v_rcp_f32_e32 v7, v6
	v_div_scale_f32 v8, vcc, v0, v2, v0
	v_fma_f32 v9, -v6, v7, 1.0
	v_fmac_f32_e32 v7, v9, v7
	v_mul_f32_e32 v9, v8, v7
	v_fma_f32 v10, -v6, v9, v8
	v_fmac_f32_e32 v9, v10, v7
	v_fma_f32 v6, -v6, v9, v8
	v_div_fmas_f32 v6, v6, v7, v9
	v_div_fixup_f32 v0, v6, v2, v0
	ds_write_b32 v5, v0
	v_add_u32_e32 v5, 0x800, v5
	v_mov_b32_e32 v6, v3
	s_andn2_b64 exec, exec, s[0:1]
	s_cbranch_execz .LBB0_26

; #define LAS __attribute__((address_space(3)))
; __device__ __forceinline__ unsigned pk2(float lo, float hi) { unsigned r; asm("v_cvt_pk_bf16_f32 %0, %1, %2" : "=v"(r) : "v"(lo), "v"(hi)); return r; }
; __device__ __forceinline__ void transpose_item(const float* W, int ldw, bf16_t* WT, int ldo, LAS float* scr, int k0, int n0, int lane, const float* rs = nullptr) {
; #pragma unroll 8
;     for (int i = 0; i < 32; ++i) { const int kk = 2 * i + (lane >> 5); scr[kk * 33 + (lane & 31)] = W[(size_t)(k0 + kk) * ldw + n0 + (lane & 31)]; }
;     asm volatile("s_waitcnt lgkmcnt(0)" ::: "memory");
;     const int c = lane & 7;
; #pragma unroll
;     for (int j = 0; j < 4; ++j) { const int n = (lane >> 3) + 8 * j; const LAS float* s = scr + (8 * c) * 33 + n; const float m = rs ? rs[n0 + n] : 1.f;
;         u32x4 o; o.x = pk2(s[0 * 33] * m, s[1 * 33] * m); o.y = pk2(s[2 * 33] * m, s[3 * 33] * m); o.z = pk2(s[4 * 33] * m, s[5 * 33] * m); o.w = pk2(s[6 * 33] * m, s[7 * 33] * m);
;         *(u32x4*)(WT + (size_t)(n0 + n) * ldo + k0 + 8 * c) = o; }
;     asm volatile("s_waitcnt lgkmcnt(0)" ::: "memory");
; }
; __device__ __forceinline__ void transpose_matrix(const float* W, int K, int N, bf16_t* WT, int ldo, LAS float* scr, int gw, int ngw, int lane, const float* rs = nullptr) {
;     const int nblk = N / 32, nitems = (K / 64) * nblk;
;     for (int it = gw; it < nitems; it += ngw) { const int kb = it / nblk, nb = it % nblk; transpose_item(W, N, WT, ldo, scr, kb * 64, nb * 32, lane, rs); }
.LBB0_34:
	s_lshl_b32 s18, s17, 1
	s_lshl_b32 s19, s16, 1
	v_or_b32_e32 v7, s18, v1
	v_or_b32_e32 v9, s19, v0
	s_add_i32 s20, s18, 4
	s_add_i32 s21, s19, 4
	s_add_i32 s23, s18, 8
	s_add_i32 s24, s19, 8
	s_add_i32 s25, s18, 12
	s_add_i32 s26, s19, 12
	s_add_i32 s27, s18, 16
	s_add_i32 s28, s19, 16
	s_add_i32 s29, s18, 20
	s_add_i32 s30, s19, 20
	s_add_i32 s31, s18, 24
	s_add_i32 s33, s19, 24
	s_add_i32 s18, s18, 28
	s_add_i32 s19, s19, 28
	v_add_u32_e32 v15, v7, v3
	v_add_u32_e32 v17, v9, v16
	v_or_b32_e32 v49, s20, v1
	v_or_b32_e32 v58, s21, v0
	v_or_b32_e32 v59, s23, v1
	v_or_b32_e32 v60, s24, v0
	v_or_b32_e32 v61, s25, v1
	v_or_b32_e32 v62, s26, v0
	v_or_b32_e32 v63, s27, v1
	v_or_b32_e32 v64, s28, v0
	v_or_b32_e32 v65, s29, v1
	v_or_b32_e32 v66, s30, v0
	v_or_b32_e32 v67, s31, v1
	v_or_b32_e32 v68, s33, v0
	v_or_b32_e32 v69, s18, v1
	v_or_b32_e32 v70, s19, v0
	v_mad_i64_i32 v[24:25], s[18:19], v17, s10, v[18:19]
	v_mad_i64_i32 v[26:27], s[18:19], v15, s10, v[18:19]
	v_add_u32_e32 v15, v49, v3
	v_add_u32_e32 v17, v58, v16
	v_add_u32_e32 v34, v59, v3
	v_add_u32_e32 v32, v60, v16
	v_add_u32_e32 v38, v61, v3
	v_add_u32_e32 v36, v62, v16
	v_add_u32_e32 v42, v63, v3
	v_add_u32_e32 v40, v64, v16
	v_add_u32_e32 v46, v65, v3
	v_add_u32_e32 v44, v66, v16
	v_add_u32_e32 v52, v67, v3
	v_add_u32_e32 v50, v68, v16
	v_add_u32_e32 v56, v69, v3
	v_add_u32_e32 v54, v70, v16
	v_mad_i64_i32 v[28:29], s[18:19], v17, s10, v[18:19]
	v_mad_i64_i32 v[30:31], s[18:19], v15, s10, v[18:19]
	v_mad_i64_i32 v[32:33], s[18:19], v32, s10, v[18:19]
	v_mad_i64_i32 v[34:35], s[18:19], v34, s10, v[18:19]
	v_mad_i64_i32 v[36:37], s[18:19], v36, s10, v[18:19]
	v_mad_i64_i32 v[38:39], s[18:19], v38, s10, v[18:19]
	v_mad_i64_i32 v[40:41], s[18:19], v40, s10, v[18:19]
	v_mad_i64_i32 v[42:43], s[18:19], v42, s10, v[18:19]
	v_mad_i64_i32 v[44:45], s[18:19], v44, s10, v[18:19]
	v_mad_i64_i32 v[46:47], s[18:19], v46, s10, v[18:19]
	v_mad_i64_i32 v[50:51], s[18:19], v50, s10, v[18:19]
	v_mad_i64_i32 v[52:53], s[18:19], v52, s10, v[18:19]
	v_mad_i64_i32 v[54:55], s[18:19], v54, s10, v[18:19]
	v_mad_i64_i32 v[56:57], s[18:19], v56, s10, v[18:19]
	global_load_dword v15, v[24:25], off nt
	global_load_dword v17, v[26:27], off nt
	global_load_dword v71, v[28:29], off nt
	global_load_dword v72, v[30:31], off nt
	global_load_dword v73, v[32:33], off nt
	global_load_dword v74, v[34:35], off nt
	global_load_dword v75, v[36:37], off nt
	global_load_dword v76, v[38:39], off nt
	global_load_dword v77, v[40:41], off nt
	global_load_dword v78, v[42:43], off nt
	global_load_dword v79, v[44:45], off nt
	global_load_dword v80, v[46:47], off nt
	global_load_dword v81, v[50:51], off nt
	global_load_dword v82, v[52:53], off nt
	global_load_dword v83, v[54:55], off nt
	global_load_dword v84, v[56:57], off nt
	s_add_i32 s16, s16, 16
	s_add_i32 s17, s17, 16
	s_add_i32 s15, s15, -16
	v_mad_u64_u32 v[24:25], s[18:19], v9, s11, v[4:5]
	s_cmp_lg_u32 s15, 0
	v_mad_u64_u32 v[26:27], s[18:19], v7, s11, v[4:5]
	v_mad_u64_u32 v[28:29], s[18:19], v58, s11, v[4:5]
	v_mad_u64_u32 v[30:31], s[18:19], v49, s11, v[4:5]
	v_mad_u64_u32 v[32:33], s[18:19], v60, s11, v[4:5]
	v_mad_u64_u32 v[34:35], s[18:19], v59, s11, v[4:5]
	v_mad_u64_u32 v[36:37], s[18:19], v62, s11, v[4:5]
	v_mad_u64_u32 v[38:39], s[18:19], v61, s11, v[4:5]
	v_mad_u64_u32 v[40:41], s[18:19], v64, s11, v[4:5]
	v_mad_u64_u32 v[42:43], s[18:19], v63, s11, v[4:5]
	v_mad_u64_u32 v[44:45], s[18:19], v66, s11, v[4:5]
	v_mad_u64_u32 v[46:47], s[18:19], v65, s11, v[4:5]
	v_mad_u64_u32 v[50:51], s[18:19], v68, s11, v[4:5]
	v_mad_u64_u32 v[52:53], s[18:19], v67, s11, v[4:5]
	v_mad_u64_u32 v[54:55], s[18:19], v70, s11, v[4:5]
	v_mad_u64_u32 v[56:57], s[18:19], v69, s11, v[4:5]
	s_waitcnt vmcnt(15)
	ds_write_b32 v24, v15
	s_waitcnt vmcnt(14)
	ds_write_b32 v26, v17
	s_waitcnt vmcnt(13)
	ds_write_b32 v28, v71
	s_waitcnt vmcnt(12)
	ds_write_b32 v30, v72
	s_waitcnt vmcnt(11)
	ds_write_b32 v32, v73
	s_waitcnt vmcnt(10)
	ds_write_b32 v34, v74
	s_waitcnt vmcnt(9)
	ds_write_b32 v36, v75
	s_waitcnt vmcnt(8)
	ds_write_b32 v38, v76
	s_waitcnt vmcnt(7)
	ds_write_b32 v40, v77
	s_waitcnt vmcnt(6)
	ds_write_b32 v42, v78
	s_waitcnt vmcnt(5)
	ds_write_b32 v44, v79
	s_waitcnt vmcnt(4)
	ds_write_b32 v46, v80
	s_waitcnt vmcnt(3)
	ds_write_b32 v50, v81
	s_waitcnt vmcnt(2)
	ds_write_b32 v52, v82
	s_waitcnt vmcnt(1)
	ds_write_b32 v54, v83
	s_waitcnt vmcnt(0)
	ds_write_b32 v56, v84
	s_cbranch_scc1 .LBB0_34
	s_waitcnt lgkmcnt(0)
	ds_read2_b32 v[28:29], v22 offset0:33 offset1:41
	ds_read2_b32 v[30:31], v22 offset1:8
	ds_read2_b32 v[32:33], v22 offset0:66 offset1:74
	ds_read2_b32 v[34:35], v22 offset0:99 offset1:107
	ds_read2_b32 v[36:37], v22 offset0:132 offset1:140
	ds_read2_b32 v[38:39], v22 offset0:165 offset1:173
	ds_read2_b32 v[40:41], v22 offset0:198 offset1:206
	ds_read2_b32 v[42:43], v22 offset0:231 offset1:239
	v_or_b32_e32 v26, v14, v2
	v_ashrrev_i32_e32 v17, 31, v16
	v_ashrrev_i32_e32 v27, 31, v26
	v_lshl_add_u64 v[24:25], v[16:17], 1, v[12:13]
	v_lshlrev_b64 v[26:27], 12, v[26:27]
	v_lshl_add_u64 v[26:27], v[24:25], 0, v[26:27]
	s_waitcnt lgkmcnt(6)
	v_cvt_pk_bf16_f32 v16, v30, v28
	s_waitcnt lgkmcnt(4)
	v_cvt_pk_bf16_f32 v17, v32, v34
	s_waitcnt lgkmcnt(2)
	v_cvt_pk_bf16_f32 v18, v36, v38
	s_waitcnt lgkmcnt(0)
	v_cvt_pk_bf16_f32 v19, v40, v42
	global_store_dwordx4 v[26:27], v[16:19], off
	v_or_b32_e32 v26, v14, v20
	v_ashrrev_i32_e32 v27, 31, v26
	v_lshlrev_b64 v[26:27], 12, v[26:27]
	v_lshl_add_u64 v[26:27], v[24:25], 0, v[26:27]
	v_cvt_pk_bf16_f32 v16, v31, v29
	v_cvt_pk_bf16_f32 v17, v33, v35
	v_cvt_pk_bf16_f32 v18, v37, v39
	v_cvt_pk_bf16_f32 v19, v41, v43
	global_store_dwordx4 v[26:27], v[16:19], off
	ds_read2_b32 v[28:29], v22 offset0:16 offset1:24
	ds_read2_b32 v[30:31], v22 offset0:49 offset1:57
	ds_read2_b32 v[32:33], v22 offset0:82 offset1:90
	ds_read2_b32 v[34:35], v22 offset0:115 offset1:123
	ds_read2_b32 v[36:37], v22 offset0:148 offset1:156
	ds_read2_b32 v[38:39], v22 offset0:181 offset1:189
	ds_read2_b32 v[40:41], v22 offset0:214 offset1:222
	ds_read2_b32 v[42:43], v22 offset0:247 offset1:255
	v_or_b32_e32 v26, v14, v23
	v_ashrrev_i32_e32 v27, 31, v26
	v_lshlrev_b64 v[26:27], 12, v[26:27]
	s_waitcnt lgkmcnt(2)
	v_cvt_pk_bf16_f32 v18, v36, v38
	v_lshl_add_u64 v[26:27], v[24:25], 0, v[26:27]
	v_cvt_pk_bf16_f32 v16, v28, v30
	v_cvt_pk_bf16_f32 v17, v32, v34
	s_waitcnt lgkmcnt(0)
	v_cvt_pk_bf16_f32 v19, v40, v42
	global_store_dwordx4 v[26:27], v[16:19], off
	v_cvt_pk_bf16_f32 v15, v33, v35
	v_add_u32_e32 v5, s22, v5
	v_cmp_lt_i32_e32 vcc, s14, v5
	v_or_b32_e32 v18, v14, v21
	v_ashrrev_i32_e32 v19, 31, v18
	v_lshlrev_b64 v[18:19], 12, v[18:19]
	v_lshl_add_u64 v[18:19], v[24:25], 0, v[18:19]
	v_cvt_pk_bf16_f32 v14, v29, v31
	v_cvt_pk_bf16_f32 v16, v37, v39
	v_cvt_pk_bf16_f32 v17, v41, v43
	global_store_dwordx4 v[18:19], v[14:17], off
	s_waitcnt lgkmcnt(0)
	s_or_b64 s[4:5], vcc, s[4:5]
	s_andn2_b64 exec, exec, s[4:5]
	s_cbranch_execnz .LBB0_33
	s_or_b64 exec, exec, s[4:5]

; #define LAS __attribute__((address_space(3)))
;     __device__ __forceinline__ const float* in(int i) const { return (const float*)(const __attribute__((address_space(1))) float*)ld(i); }
;     __device__ __forceinline__ unsigned char* wsp() const { return (unsigned char*)(__attribute__((address_space(1))) unsigned char*)ld(33); }
; __device__ __forceinline__ void transpose_item(const float* W, int ldw, bf16_t* WT, int ldo, LAS float* scr, int k0, int n0, int lane, const float* rs = nullptr) {
; #pragma unroll 8
;     for (int i = 0; i < 32; ++i) { const int kk = 2 * i + (lane >> 5); scr[kk * 33 + (lane & 31)] = W[(size_t)(k0 + kk) * ldw + n0 + (lane & 31)]; }
;     asm volatile("s_waitcnt lgkmcnt(0)" ::: "memory");
;     const int c = lane & 7;
; #pragma unroll
;     for (int j = 0; j < 4; ++j) { const int n = (lane >> 3) + 8 * j; const LAS float* s = scr + (8 * c) * 33 + n; const float m = rs ? rs[n0 + n] : 1.f;
; __device__ __forceinline__ void phase_convert(const DArgs& a, LAS unsigned char* lds) {
;     ...
;     for (int g = 0; g < 4; ++g) transpose_matrix(a.in(I_WPOOL) + (size_t)g * 65536, 256, 256, (bf16_t*)(a.wsp() + W_POOLT) + (size_t)g * 65536, 256, scr, gw, ngw, lane, a.in(I_PSCALE) + g * 256);
.LBB0_43:
	s_lshl_b32 s25, s0, 1
	s_lshl_b32 s26, s1, 1
	v_or_b32_e32 v17, s25, v1
	v_or_b32_e32 v49, s26, v0
	s_add_i32 s27, s25, 4
	s_add_i32 s28, s26, 4
	s_add_i32 s29, s25, 8
	s_add_i32 s30, s26, 8
	s_add_i32 s31, s25, 12
	s_add_i32 s33, s26, 12
	s_add_i32 s34, s25, 16
	s_add_i32 s35, s26, 16
	s_add_i32 s36, s25, 20
	s_add_i32 s37, s26, 20
	s_add_i32 s38, s25, 24
	s_add_i32 s39, s26, 24
	s_add_i32 s25, s25, 28
	s_add_i32 s26, s26, 28
	v_add_u32_e32 v28, v49, v16
	v_or_b32_e32 v60, s27, v1
	v_or_b32_e32 v61, s28, v0
	v_or_b32_e32 v62, s29, v1
	v_or_b32_e32 v63, s30, v0
	v_or_b32_e32 v64, s31, v1
	v_or_b32_e32 v65, s33, v0
	v_or_b32_e32 v66, s34, v1
	v_or_b32_e32 v67, s35, v0
	v_or_b32_e32 v68, s36, v1
	v_or_b32_e32 v69, s37, v0
	v_or_b32_e32 v70, s38, v1
	v_or_b32_e32 v71, s39, v0
	v_or_b32_e32 v72, s25, v1
	v_or_b32_e32 v73, s26, v0
	v_add_u32_e32 v26, v17, v5
	v_ashrrev_i32_e32 v29, 31, v28
	v_add_u32_e32 v30, v60, v5
	v_add_u32_e32 v32, v61, v16
	v_add_u32_e32 v34, v62, v5
	v_add_u32_e32 v36, v63, v16
	v_add_u32_e32 v38, v64, v5
	v_add_u32_e32 v40, v65, v16
	v_add_u32_e32 v42, v66, v5
	v_add_u32_e32 v44, v67, v16
	v_add_u32_e32 v46, v68, v5
	v_add_u32_e32 v50, v69, v16
	v_add_u32_e32 v52, v70, v5
	v_add_u32_e32 v54, v71, v16
	v_add_u32_e32 v56, v72, v5
	v_add_u32_e32 v58, v73, v16
	v_ashrrev_i32_e32 v27, 31, v26
	v_lshlrev_b64 v[28:29], 10, v[28:29]
	v_ashrrev_i32_e32 v33, 31, v32
	v_ashrrev_i32_e32 v31, 31, v30
	v_ashrrev_i32_e32 v37, 31, v36
	v_ashrrev_i32_e32 v35, 31, v34
	v_ashrrev_i32_e32 v41, 31, v40
	v_ashrrev_i32_e32 v39, 31, v38
	v_ashrrev_i32_e32 v45, 31, v44
	v_ashrrev_i32_e32 v43, 31, v42
	v_ashrrev_i32_e32 v51, 31, v50
	v_ashrrev_i32_e32 v47, 31, v46
	v_ashrrev_i32_e32 v55, 31, v54
	v_ashrrev_i32_e32 v53, 31, v52
	v_ashrrev_i32_e32 v59, 31, v58
	v_ashrrev_i32_e32 v57, 31, v56
	v_lshlrev_b64 v[26:27], 10, v[26:27]
	v_lshl_add_u64 v[28:29], v[18:19], 0, v[28:29]
	v_lshlrev_b64 v[30:31], 10, v[30:31]
	v_lshlrev_b64 v[32:33], 10, v[32:33]
	v_lshlrev_b64 v[34:35], 10, v[34:35]
	v_lshlrev_b64 v[36:37], 10, v[36:37]
	v_lshlrev_b64 v[38:39], 10, v[38:39]
	v_lshlrev_b64 v[40:41], 10, v[40:41]
	v_lshlrev_b64 v[42:43], 10, v[42:43]
	v_lshlrev_b64 v[44:45], 10, v[44:45]
	v_lshlrev_b64 v[46:47], 10, v[46:47]
	v_lshlrev_b64 v[50:51], 10, v[50:51]
	v_lshlrev_b64 v[52:53], 10, v[52:53]
	v_lshlrev_b64 v[54:55], 10, v[54:55]
	v_lshlrev_b64 v[56:57], 10, v[56:57]
	v_lshlrev_b64 v[58:59], 10, v[58:59]
	v_lshl_add_u64 v[26:27], v[18:19], 0, v[26:27]
	v_lshl_add_u64 v[32:33], v[18:19], 0, v[32:33]
	v_lshl_add_u64 v[30:31], v[18:19], 0, v[30:31]
	v_lshl_add_u64 v[36:37], v[18:19], 0, v[36:37]
	v_lshl_add_u64 v[34:35], v[18:19], 0, v[34:35]
	v_lshl_add_u64 v[40:41], v[18:19], 0, v[40:41]
	v_lshl_add_u64 v[38:39], v[18:19], 0, v[38:39]
	v_lshl_add_u64 v[44:45], v[18:19], 0, v[44:45]
	v_lshl_add_u64 v[42:43], v[18:19], 0, v[42:43]
	v_lshl_add_u64 v[50:51], v[18:19], 0, v[50:51]
	v_lshl_add_u64 v[46:47], v[18:19], 0, v[46:47]
	v_lshl_add_u64 v[54:55], v[18:19], 0, v[54:55]
	v_lshl_add_u64 v[52:53], v[18:19], 0, v[52:53]
	v_lshl_add_u64 v[58:59], v[18:19], 0, v[58:59]
	v_lshl_add_u64 v[56:57], v[18:19], 0, v[56:57]
	global_load_dword v74, v[28:29], off nt
	global_load_dword v75, v[26:27], off nt
	global_load_dword v76, v[32:33], off nt
	global_load_dword v77, v[30:31], off nt
	global_load_dword v78, v[36:37], off nt
	global_load_dword v79, v[34:35], off nt
	global_load_dword v80, v[40:41], off nt
	global_load_dword v81, v[38:39], off nt
	global_load_dword v82, v[44:45], off nt
	global_load_dword v83, v[42:43], off nt
	global_load_dword v84, v[50:51], off nt
	global_load_dword v85, v[46:47], off nt
	global_load_dword v86, v[54:55], off nt
	global_load_dword v87, v[52:53], off nt
	global_load_dword v88, v[58:59], off nt
	global_load_dword v89, v[56:57], off nt
	s_add_i32 s1, s1, 16
	s_add_i32 s0, s0, 16
	s_add_i32 s8, s8, -16
	v_mad_u64_u32 v[26:27], s[26:27], v49, s23, v[4:5]
	s_cmp_lg_u32 s8, 0
	v_mad_u64_u32 v[28:29], s[26:27], v17, s23, v[4:5]
	v_mad_u64_u32 v[30:31], s[26:27], v61, s23, v[4:5]
	v_mad_u64_u32 v[32:33], s[26:27], v60, s23, v[4:5]
	v_mad_u64_u32 v[34:35], s[26:27], v63, s23, v[4:5]
	v_mad_u64_u32 v[36:37], s[26:27], v62, s23, v[4:5]
	v_mad_u64_u32 v[38:39], s[26:27], v65, s23, v[4:5]
	v_mad_u64_u32 v[40:41], s[26:27], v64, s23, v[4:5]
	v_mad_u64_u32 v[42:43], s[26:27], v67, s23, v[4:5]
	v_mad_u64_u32 v[44:45], s[26:27], v66, s23, v[4:5]
	v_mad_u64_u32 v[46:47], s[26:27], v69, s23, v[4:5]
	v_mad_u64_u32 v[50:51], s[26:27], v68, s23, v[4:5]
	v_mad_u64_u32 v[52:53], s[26:27], v71, s23, v[4:5]
	v_mad_u64_u32 v[54:55], s[26:27], v70, s23, v[4:5]
	v_mad_u64_u32 v[56:57], s[26:27], v73, s23, v[4:5]
	v_mad_u64_u32 v[58:59], s[26:27], v72, s23, v[4:5]
	s_waitcnt vmcnt(15)
	ds_write_b32 v26, v74
	s_waitcnt vmcnt(14)
	ds_write_b32 v28, v75
	s_waitcnt vmcnt(13)
	ds_write_b32 v30, v76
	s_waitcnt vmcnt(12)
	ds_write_b32 v32, v77
	s_waitcnt vmcnt(11)
	ds_write_b32 v34, v78
	s_waitcnt vmcnt(10)
	ds_write_b32 v36, v79
	s_waitcnt vmcnt(9)
	ds_write_b32 v38, v80
	s_waitcnt vmcnt(8)
	ds_write_b32 v40, v81
	s_waitcnt vmcnt(7)
	ds_write_b32 v42, v82
	s_waitcnt vmcnt(6)
	ds_write_b32 v44, v83
	s_waitcnt vmcnt(5)
	ds_write_b32 v46, v84
	s_waitcnt vmcnt(4)
	ds_write_b32 v50, v85
	s_waitcnt vmcnt(3)
	ds_write_b32 v52, v86
	s_waitcnt vmcnt(2)
	ds_write_b32 v54, v87
	s_waitcnt vmcnt(1)
	ds_write_b32 v56, v88
	s_waitcnt vmcnt(0)
	ds_write_b32 v58, v89
	s_cbranch_scc1 .LBB0_43
	s_waitcnt lgkmcnt(0)
	v_or_b32_e32 v18, v14, v2
	v_cndmask_b32_e64 v17, 0, 1, s[20:21]
	v_ashrrev_i32_e32 v19, 31, v18
	v_mov_b32_e32 v5, 1.0
	v_cmp_ne_u32_e64 s[0:1], 1, v17
	s_andn2_b64 vcc, exec, s[20:21]
	v_mov_b32_e32 v26, 1.0
	s_cbranch_vccnz .LBB0_46
	v_lshl_add_u64 v[26:27], v[18:19], 2, s[16:17]
	global_load_dword v26, v[26:27], off nt
; #define LAS __attribute__((address_space(3)))
; __device__ __forceinline__ unsigned pk2(float lo, float hi) { unsigned r; asm("v_cvt_pk_bf16_f32 %0, %1, %2" : "=v"(r) : "v"(lo), "v"(hi)); return r; }
; __device__ __forceinline__ void transpose_item(const float* W, int ldw, bf16_t* WT, int ldo, LAS float* scr, int k0, int n0, int lane, const float* rs = nullptr) {
;     ...
;     for (int j = 0; j < 4; ++j) { const int n = (lane >> 3) + 8 * j; const LAS float* s = scr + (8 * c) * 33 + n; const float m = rs ? rs[n0 + n] : 1.f;
;         u32x4 o; o.x = pk2(s[0 * 33] * m, s[1 * 33] * m); o.y = pk2(s[2 * 33] * m, s[3 * 33] * m); o.z = pk2(s[4 * 33] * m, s[5 * 33] * m); o.w = pk2(s[6 * 33] * m, s[7 * 33] * m);
;         *(u32x4*)(WT + (size_t)(n0 + n) * ldo + k0 + 8 * c) = o; }
.LBB0_46:
	ds_read2_b32 v[28:29], v22 offset1:33
	ds_read2_b32 v[30:31], v22 offset0:66 offset1:99
	ds_read2_b32 v[32:33], v22 offset0:132 offset1:165
	ds_read2_b32 v[34:35], v22 offset0:198 offset1:231
	v_ashrrev_i32_e32 v17, 31, v16
	s_waitcnt vmcnt(0) lgkmcnt(3)
	v_mul_f32_e32 v27, v26, v28
	v_mul_f32_e32 v28, v26, v29
	v_lshl_add_u64 v[16:17], v[16:17], 1, v[12:13]
	v_cvt_pk_bf16_f32 v28, v27, v28
	s_waitcnt lgkmcnt(2)
	v_mul_f32_e32 v27, v26, v30
	v_mul_f32_e32 v29, v26, v31
	v_lshlrev_b64 v[18:19], 9, v[18:19]
	v_cvt_pk_bf16_f32 v29, v27, v29
	s_waitcnt lgkmcnt(1)
	v_mul_f32_e32 v27, v26, v32
	v_mul_f32_e32 v30, v26, v33
	v_lshl_add_u64 v[18:19], v[16:17], 0, v[18:19]
	v_cvt_pk_bf16_f32 v30, v27, v30
	s_waitcnt lgkmcnt(0)
	v_mul_f32_e32 v27, v26, v34
	v_mul_f32_e32 v26, v26, v35
	v_cvt_pk_bf16_f32 v31, v27, v26
	global_store_dwordx4 v[18:19], v[28:31], off
	v_lshl_add_u64 v[18:19], v[14:15], 0, v[2:3]
	s_and_b64 vcc, exec, s[0:1]
	v_lshl_add_u64 v[18:19], v[18:19], 2, s[16:17]
	s_cbranch_vccnz .LBB0_48
	global_load_dword v5, v[18:19], off offset:32 nt
.LBB0_48:
	ds_read2_b32 v[26:27], v22 offset0:8 offset1:41
	ds_read2_b32 v[28:29], v22 offset0:74 offset1:107
	ds_read2_b32 v[32:33], v22 offset0:140 offset1:173
	ds_read2_b32 v[34:35], v22 offset0:206 offset1:239
	v_or_b32_e32 v30, v14, v20
	s_waitcnt vmcnt(0) lgkmcnt(3)
	v_mul_f32_e32 v15, v5, v26
	v_mul_f32_e32 v26, v5, v27
	v_cvt_pk_bf16_f32 v26, v15, v26
	s_waitcnt lgkmcnt(2)
	v_mul_f32_e32 v15, v5, v28
	v_mul_f32_e32 v27, v5, v29
	v_ashrrev_i32_e32 v31, 31, v30
	v_cvt_pk_bf16_f32 v27, v15, v27
	s_waitcnt lgkmcnt(1)
	v_mul_f32_e32 v15, v5, v32
	v_mul_f32_e32 v28, v5, v33
	v_cvt_pk_bf16_f32 v28, v15, v28
	s_waitcnt lgkmcnt(0)
	v_mul_f32_e32 v15, v5, v34
	v_mul_f32_e32 v5, v5, v35
	v_lshlrev_b64 v[30:31], 9, v[30:31]
	v_cvt_pk_bf16_f32 v29, v15, v5
	v_lshl_add_u64 v[30:31], v[16:17], 0, v[30:31]
	v_mov_b32_e32 v5, 1.0
	s_and_b64 vcc, exec, s[0:1]
	v_mov_b32_e32 v15, 1.0
	global_store_dwordx4 v[30:31], v[26:29], off
	s_cbranch_vccnz .LBB0_50
	global_load_dword v15, v[18:19], off offset:64 nt
.LBB0_50:
	ds_read2_b32 v[26:27], v22 offset0:16 offset1:49
	ds_read2_b32 v[28:29], v22 offset0:82 offset1:115
	ds_read2_b32 v[32:33], v22 offset0:148 offset1:181
	ds_read2_b32 v[34:35], v22 offset0:214 offset1:247
	v_or_b32_e32 v30, v14, v23
	s_waitcnt vmcnt(0) lgkmcnt(3)
	v_mul_f32_e32 v26, v15, v26
	v_mul_f32_e32 v27, v15, v27
	v_ashrrev_i32_e32 v31, 31, v30
	v_cvt_pk_bf16_f32 v26, v26, v27
	s_waitcnt lgkmcnt(2)
	v_mul_f32_e32 v27, v15, v28
	v_mul_f32_e32 v28, v15, v29
	v_cvt_pk_bf16_f32 v27, v27, v28
	s_waitcnt lgkmcnt(1)
	v_mul_f32_e32 v28, v15, v32
	v_mul_f32_e32 v29, v15, v33
	v_lshlrev_b64 v[30:31], 9, v[30:31]
	v_cvt_pk_bf16_f32 v28, v28, v29
	s_waitcnt lgkmcnt(0)
	v_mul_f32_e32 v29, v15, v34
	v_lshl_add_u64 v[30:31], v[16:17], 0, v[30:31]
	s_and_b64 vcc, exec, s[0:1]
	v_mul_f32_e32 v15, v15, v35
	v_cvt_pk_bf16_f32 v29, v29, v15
	global_store_dwordx4 v[30:31], v[26:29], off
	s_cbranch_vccnz .LBB0_41
	global_load_dword v5, v[18:19], off offset:96 nt
	s_branch .LBB0_41

;     __device__ __forceinline__ const float* in(int i) const { return (const float*)(const __attribute__((address_space(1))) float*)ld(i); }
; __device__ __forceinline__ bf16_t f2bf(float f) { return (bf16_t)(pk2(f, 0.f) & 0xffffu); }
; __device__ __forceinline__ void phase_convert(const DArgs& a, LAS unsigned char* lds) {
;     ...
;     for (int i = blockIdx.x * NTHR + threadIdx.x; i < 3072 * 256; i += gridDim.x * NTHR) {
;         const int row = i >> 8, k = i & 255, part = row >> 10, n = row & 1023; float v = 0.f;
;         if (part == 0) { if (k < 64) v = a.in(I_W2)[k * 1024 + n]; }
;         else if (part == 1) { if (k >= 64 && k < 128) v = a.in(I_A2)[(k - 64) * 1024 + n]; }
;         else { if (k >= 128) v = a.in(I_G2)[(k - 128) * 1024 + n]; }
;         lt[i] = f2bf(v);
.LBB0_70:
	v_lshl_add_u64 v[4:5], v[2:3], 2, v[4:5]
	global_load_dword v1, v[4:5], off nt
	s_branch .LBB0_54

; #define LAS __attribute__((address_space(3)))
;     __device__ __forceinline__ const float* in(int i) const { return (const float*)(const __attribute__((address_space(1))) float*)ld(i); }
; __device__ __forceinline__ void transpose_item(const float* W, int ldw, bf16_t* WT, int ldo, LAS float* scr, int k0, int n0, int lane, const float* rs = nullptr) {
; #pragma unroll 8
;     for (int i = 0; i < 32; ++i) { const int kk = 2 * i + (lane >> 5); scr[kk * 33 + (lane & 31)] = W[(size_t)(k0 + kk) * ldw + n0 + (lane & 31)]; }
;     asm volatile("s_waitcnt lgkmcnt(0)" ::: "memory");
; __device__ __forceinline__ void convert_sub(const DArgs& a, LAS unsigned char* lds, int which, int c0) {
;     ...
;     case CV_OUT0: transpose_matrix(a.in(I_WOUT0), D, D, (bf16_t*)(w + W_OUT0T), D, scr, gw, ngw, lane); break;
.LBB0_273:
	s_lshl_b32 s16, s15, 1
	s_lshl_b32 s17, s9, 1
	v_or_b32_e32 v7, s16, v1
	v_or_b32_e32 v13, s17, v0
	s_add_i32 s18, s16, 4
	s_add_i32 s19, s17, 4
	s_add_i32 s20, s16, 8
	s_add_i32 s21, s17, 8
	s_add_i32 s22, s16, 12
	s_add_i32 s23, s17, 12
	s_add_i32 s24, s16, 16
	s_add_i32 s25, s17, 16
	s_add_i32 s26, s16, 20
	s_add_i32 s27, s17, 20
	s_add_i32 s28, s16, 24
	s_add_i32 s29, s17, 24
	s_add_i32 s16, s16, 28
	s_add_i32 s17, s17, 28
	v_add_u32_e32 v26, v13, v14
	v_or_b32_e32 v15, s18, v1
	v_or_b32_e32 v56, s19, v0
	v_or_b32_e32 v57, s20, v1
	v_or_b32_e32 v58, s21, v0
	v_or_b32_e32 v59, s22, v1
	v_or_b32_e32 v60, s23, v0
	v_or_b32_e32 v61, s24, v1
	v_or_b32_e32 v62, s25, v0
	v_or_b32_e32 v63, s26, v1
	v_or_b32_e32 v64, s27, v0
	v_or_b32_e32 v65, s28, v1
	v_or_b32_e32 v66, s29, v0
	v_or_b32_e32 v67, s16, v1
	v_or_b32_e32 v68, s17, v0
	v_add_u32_e32 v24, v7, v3
	v_ashrrev_i32_e32 v27, 31, v26
	v_add_u32_e32 v28, v15, v3
	v_add_u32_e32 v30, v56, v14
	v_add_u32_e32 v32, v57, v3
	v_add_u32_e32 v34, v58, v14
	v_add_u32_e32 v36, v59, v3
	v_add_u32_e32 v38, v60, v14
	v_add_u32_e32 v40, v61, v3
	v_add_u32_e32 v42, v62, v14
	v_add_u32_e32 v44, v63, v3
	v_add_u32_e32 v46, v64, v14
	v_add_u32_e32 v48, v65, v3
	v_add_u32_e32 v50, v66, v14
	v_add_u32_e32 v52, v67, v3
	v_add_u32_e32 v54, v68, v14
	v_ashrrev_i32_e32 v25, 31, v24
	v_lshlrev_b64 v[26:27], 13, v[26:27]
	v_ashrrev_i32_e32 v31, 31, v30
	v_ashrrev_i32_e32 v29, 31, v28
	v_ashrrev_i32_e32 v35, 31, v34
	v_ashrrev_i32_e32 v33, 31, v32
	v_ashrrev_i32_e32 v39, 31, v38
	v_ashrrev_i32_e32 v37, 31, v36
	v_ashrrev_i32_e32 v43, 31, v42
	v_ashrrev_i32_e32 v41, 31, v40
	v_ashrrev_i32_e32 v47, 31, v46
	v_ashrrev_i32_e32 v45, 31, v44
	v_ashrrev_i32_e32 v51, 31, v50
	v_ashrrev_i32_e32 v49, 31, v48
	v_ashrrev_i32_e32 v55, 31, v54
	v_ashrrev_i32_e32 v53, 31, v52
	v_lshlrev_b64 v[24:25], 13, v[24:25]
	v_lshl_add_u64 v[26:27], v[16:17], 0, v[26:27]
	v_lshlrev_b64 v[28:29], 13, v[28:29]
	v_lshlrev_b64 v[30:31], 13, v[30:31]
	v_lshlrev_b64 v[32:33], 13, v[32:33]
	v_lshlrev_b64 v[34:35], 13, v[34:35]
	v_lshlrev_b64 v[36:37], 13, v[36:37]
	v_lshlrev_b64 v[38:39], 13, v[38:39]
	v_lshlrev_b64 v[40:41], 13, v[40:41]
	v_lshlrev_b64 v[42:43], 13, v[42:43]
	v_lshlrev_b64 v[44:45], 13, v[44:45]
	v_lshlrev_b64 v[46:47], 13, v[46:47]
	v_lshlrev_b64 v[48:49], 13, v[48:49]
	v_lshlrev_b64 v[50:51], 13, v[50:51]
	v_lshlrev_b64 v[52:53], 13, v[52:53]
	v_lshlrev_b64 v[54:55], 13, v[54:55]
	v_lshl_add_u64 v[24:25], v[16:17], 0, v[24:25]
	v_lshl_add_u64 v[30:31], v[16:17], 0, v[30:31]
	v_lshl_add_u64 v[28:29], v[16:17], 0, v[28:29]
	v_lshl_add_u64 v[34:35], v[16:17], 0, v[34:35]
	v_lshl_add_u64 v[32:33], v[16:17], 0, v[32:33]
	v_lshl_add_u64 v[38:39], v[16:17], 0, v[38:39]
	v_lshl_add_u64 v[36:37], v[16:17], 0, v[36:37]
	v_lshl_add_u64 v[42:43], v[16:17], 0, v[42:43]
	v_lshl_add_u64 v[40:41], v[16:17], 0, v[40:41]
	v_lshl_add_u64 v[46:47], v[16:17], 0, v[46:47]
	v_lshl_add_u64 v[44:45], v[16:17], 0, v[44:45]
	v_lshl_add_u64 v[50:51], v[16:17], 0, v[50:51]
	v_lshl_add_u64 v[48:49], v[16:17], 0, v[48:49]
	v_lshl_add_u64 v[54:55], v[16:17], 0, v[54:55]
	v_lshl_add_u64 v[52:53], v[16:17], 0, v[52:53]
	global_load_dword v69, v[26:27], off nt
	global_load_dword v70, v[24:25], off nt
	global_load_dword v71, v[30:31], off nt
	global_load_dword v72, v[28:29], off nt
	global_load_dword v73, v[34:35], off nt
	global_load_dword v74, v[32:33], off nt
	global_load_dword v75, v[38:39], off nt
	global_load_dword v76, v[36:37], off nt
	global_load_dword v77, v[42:43], off nt
	global_load_dword v78, v[40:41], off nt
	global_load_dword v79, v[46:47], off nt
	global_load_dword v80, v[44:45], off nt
	global_load_dword v81, v[50:51], off nt
	global_load_dword v82, v[48:49], off nt
	global_load_dword v83, v[54:55], off nt
	global_load_dword v84, v[52:53], off nt
	s_add_i32 s9, s9, 16
	s_add_i32 s15, s15, 16
	s_add_i32 s14, s14, -16
	v_mad_u64_u32 v[24:25], s[16:17], v13, s11, v[2:3]
	s_cmp_lg_u32 s14, 0
	v_mad_u64_u32 v[26:27], s[16:17], v7, s11, v[2:3]
	v_mad_u64_u32 v[28:29], s[16:17], v56, s11, v[2:3]
	v_mad_u64_u32 v[30:31], s[16:17], v15, s11, v[2:3]
	v_mad_u64_u32 v[32:33], s[16:17], v58, s11, v[2:3]
	v_mad_u64_u32 v[34:35], s[16:17], v57, s11, v[2:3]
	v_mad_u64_u32 v[36:37], s[16:17], v60, s11, v[2:3]
	v_mad_u64_u32 v[38:39], s[16:17], v59, s11, v[2:3]
	v_mad_u64_u32 v[40:41], s[16:17], v62, s11, v[2:3]
	v_mad_u64_u32 v[42:43], s[16:17], v61, s11, v[2:3]
	v_mad_u64_u32 v[44:45], s[16:17], v64, s11, v[2:3]
	v_mad_u64_u32 v[46:47], s[16:17], v63, s11, v[2:3]
	v_mad_u64_u32 v[48:49], s[16:17], v66, s11, v[2:3]
	v_mad_u64_u32 v[50:51], s[16:17], v65, s11, v[2:3]
	v_mad_u64_u32 v[52:53], s[16:17], v68, s11, v[2:3]
	v_mad_u64_u32 v[54:55], s[16:17], v67, s11, v[2:3]
	s_waitcnt vmcnt(15)
	ds_write_b32 v24, v69
	s_waitcnt vmcnt(14)
	ds_write_b32 v26, v70
	s_waitcnt vmcnt(13)
	ds_write_b32 v28, v71
	s_waitcnt vmcnt(12)
	ds_write_b32 v30, v72
	s_waitcnt vmcnt(11)
	ds_write_b32 v32, v73
	s_waitcnt vmcnt(10)
	ds_write_b32 v34, v74
	s_waitcnt vmcnt(9)
	ds_write_b32 v36, v75
	s_waitcnt vmcnt(8)
	ds_write_b32 v38, v76
	s_waitcnt vmcnt(7)
	ds_write_b32 v40, v77
	s_waitcnt vmcnt(6)
	ds_write_b32 v42, v78
	s_waitcnt vmcnt(5)
	ds_write_b32 v44, v79
	s_waitcnt vmcnt(4)
	ds_write_b32 v46, v80
	s_waitcnt vmcnt(3)
	ds_write_b32 v48, v81
	s_waitcnt vmcnt(2)
	ds_write_b32 v50, v82
	s_waitcnt vmcnt(1)
	ds_write_b32 v52, v83
	s_waitcnt vmcnt(0)
	ds_write_b32 v54, v84
	s_cbranch_scc1 .LBB0_273
; #define LAS __attribute__((address_space(3)))
;     __device__ __forceinline__ const float* in(int i) const { return (const float*)(const __attribute__((address_space(1))) float*)ld(i); }
; __device__ __forceinline__ unsigned pk2(float lo, float hi) { unsigned r; asm("v_cvt_pk_bf16_f32 %0, %1, %2" : "=v"(r) : "v"(lo), "v"(hi)); return r; }
; __device__ __forceinline__ void transpose_item(const float* W, int ldw, bf16_t* WT, int ldo, LAS float* scr, int k0, int n0, int lane, const float* rs = nullptr) {
;     ...
;     const int c = lane & 7;
; #pragma unroll
;     for (int j = 0; j < 4; ++j) { const int n = (lane >> 3) + 8 * j; const LAS float* s = scr + (8 * c) * 33 + n; const float m = rs ? rs[n0 + n] : 1.f;
;         u32x4 o; o.x = pk2(s[0 * 33] * m, s[1 * 33] * m); o.y = pk2(s[2 * 33] * m, s[3 * 33] * m); o.z = pk2(s[4 * 33] * m, s[5 * 33] * m); o.w = pk2(s[6 * 33] * m, s[7 * 33] * m);
;         *(u32x4*)(WT + (size_t)(n0 + n) * ldo + k0 + 8 * c) = o; }
;     asm volatile("s_waitcnt lgkmcnt(0)" ::: "memory");
; __device__ __forceinline__ void convert_sub(const DArgs& a, LAS unsigned char* lds, int which, int c0) {
;     ...
;     case CV_OUT0: transpose_matrix(a.in(I_WOUT0), D, D, (bf16_t*)(w + W_OUT0T), D, scr, gw, ngw, lane); break;
	s_waitcnt lgkmcnt(0)
	ds_read2_b32 v[28:29], v19 offset0:33 offset1:41
	ds_read2_b32 v[30:31], v19 offset1:8
	ds_read2_b32 v[32:33], v19 offset0:66 offset1:74
	ds_read2_b32 v[34:35], v19 offset0:99 offset1:107
	ds_read2_b32 v[36:37], v19 offset0:132 offset1:140
	ds_read2_b32 v[38:39], v19 offset0:165 offset1:173
	ds_read2_b32 v[40:41], v19 offset0:198 offset1:206
	ds_read2_b32 v[42:43], v19 offset0:231 offset1:239
	v_or_b32_e32 v26, v12, v18
	v_ashrrev_i32_e32 v15, 31, v14
	v_ashrrev_i32_e32 v27, 31, v26
	v_lshl_add_u64 v[24:25], v[14:15], 1, v[10:11]
	v_lshlrev_b64 v[26:27], 12, v[26:27]
	v_lshl_add_u64 v[26:27], v[24:25], 0, v[26:27]
	s_waitcnt lgkmcnt(6)
	v_cvt_pk_bf16_f32 v14, v30, v28
	s_waitcnt lgkmcnt(4)
	v_cvt_pk_bf16_f32 v15, v32, v34
	s_waitcnt lgkmcnt(2)
	v_cvt_pk_bf16_f32 v16, v36, v38
	s_waitcnt lgkmcnt(0)
	v_cvt_pk_bf16_f32 v17, v40, v42
	global_store_dwordx4 v[26:27], v[14:17], off
	v_or_b32_e32 v26, v12, v20
	v_ashrrev_i32_e32 v27, 31, v26
	v_lshlrev_b64 v[26:27], 12, v[26:27]
	v_lshl_add_u64 v[26:27], v[24:25], 0, v[26:27]
	v_cvt_pk_bf16_f32 v14, v31, v29
	v_cvt_pk_bf16_f32 v15, v33, v35
	v_cvt_pk_bf16_f32 v16, v37, v39
	v_cvt_pk_bf16_f32 v17, v41, v43
	global_store_dwordx4 v[26:27], v[14:17], off
	ds_read2_b32 v[28:29], v19 offset0:16 offset1:24
	ds_read2_b32 v[30:31], v19 offset0:49 offset1:57
	ds_read2_b32 v[32:33], v19 offset0:82 offset1:90
	ds_read2_b32 v[34:35], v19 offset0:115 offset1:123
	ds_read2_b32 v[36:37], v19 offset0:148 offset1:156
	ds_read2_b32 v[38:39], v19 offset0:181 offset1:189
	ds_read2_b32 v[40:41], v19 offset0:214 offset1:222
	ds_read2_b32 v[42:43], v19 offset0:247 offset1:255
	v_or_b32_e32 v26, v12, v21
	v_ashrrev_i32_e32 v27, 31, v26
	v_lshlrev_b64 v[26:27], 12, v[26:27]
	s_waitcnt lgkmcnt(2)
	v_cvt_pk_bf16_f32 v16, v36, v38
	v_lshl_add_u64 v[26:27], v[24:25], 0, v[26:27]
	v_cvt_pk_bf16_f32 v14, v28, v30
	v_cvt_pk_bf16_f32 v15, v32, v34
	s_waitcnt lgkmcnt(0)
	v_cvt_pk_bf16_f32 v17, v40, v42
	global_store_dwordx4 v[26:27], v[14:17], off
	v_cvt_pk_bf16_f32 v13, v33, v35
	v_add_u32_e32 v5, s10, v5
	v_cmp_lt_i32_e32 vcc, s8, v5
	v_or_b32_e32 v16, v12, v22
	v_ashrrev_i32_e32 v17, 31, v16
	v_lshlrev_b64 v[16:17], 12, v[16:17]
	v_lshl_add_u64 v[16:17], v[24:25], 0, v[16:17]
	v_cvt_pk_bf16_f32 v12, v29, v31
	v_cvt_pk_bf16_f32 v14, v37, v39
	v_cvt_pk_bf16_f32 v15, v41, v43
	global_store_dwordx4 v[16:17], v[12:15], off
	s_waitcnt lgkmcnt(0)
	s_or_b64 s[6:7], vcc, s[6:7]
	s_andn2_b64 exec, exec, s[6:7]
	s_cbranch_execnz .LBB0_272
	s_or_b64 exec, exec, s[6:7]
	s_add_i32 s6, 0, 0x20108
	v_mov_b32_e32 v1, s6
	ds_read_b64 v[8:9], v1

; #define LAS __attribute__((address_space(3)))
;     __device__ __forceinline__ const float* in(int i) const { return (const float*)(const __attribute__((address_space(1))) float*)ld(i); }
; __device__ __forceinline__ void transpose_item(const float* W, int ldw, bf16_t* WT, int ldo, LAS float* scr, int k0, int n0, int lane, const float* rs = nullptr) {
; #pragma unroll 8
;     for (int i = 0; i < 32; ++i) { const int kk = 2 * i + (lane >> 5); scr[kk * 33 + (lane & 31)] = W[(size_t)(k0 + kk) * ldw + n0 + (lane & 31)]; }
;     asm volatile("s_waitcnt lgkmcnt(0)" ::: "memory");
; __device__ __forceinline__ void convert_sub(const DArgs& a, LAS unsigned char* lds, int which, int c0) {
;     ...
;     case CV_FF1_0: transpose_matrix(a.in(I_WFF1), D, DFF, (bf16_t*)(w + W_FF1T), D, scr, gw, ngw, lane); break;
.LBB0_279:
	s_lshl_b32 s16, s15, 1
	s_lshl_b32 s17, s11, 1
	v_or_b32_e32 v7, s16, v1
	v_or_b32_e32 v11, s17, v0
	s_add_i32 s18, s16, 4
	s_add_i32 s19, s17, 4
	s_add_i32 s20, s16, 8
	s_add_i32 s21, s17, 8
	s_add_i32 s22, s16, 12
	s_add_i32 s23, s17, 12
	s_add_i32 s24, s16, 16
	s_add_i32 s25, s17, 16
	s_add_i32 s26, s16, 20
	s_add_i32 s27, s17, 20
	s_add_i32 s28, s16, 24
	s_add_i32 s29, s17, 24
	s_add_i32 s16, s16, 28
	s_add_i32 s17, s17, 28
	v_add_u32_e32 v16, v11, v10
	v_or_b32_e32 v52, s18, v1
	v_or_b32_e32 v53, s19, v0
	v_or_b32_e32 v54, s20, v1
	v_or_b32_e32 v55, s21, v0
	v_or_b32_e32 v56, s22, v1
	v_or_b32_e32 v57, s23, v0
	v_or_b32_e32 v58, s24, v1
	v_or_b32_e32 v59, s25, v0
	v_or_b32_e32 v60, s26, v1
	v_or_b32_e32 v61, s27, v0
	v_or_b32_e32 v62, s28, v1
	v_or_b32_e32 v63, s29, v0
	v_or_b32_e32 v64, s16, v1
	v_or_b32_e32 v65, s17, v0
	v_add_u32_e32 v14, v7, v3
	v_ashrrev_i32_e32 v17, 31, v16
	v_add_u32_e32 v24, v52, v3
	v_add_u32_e32 v26, v53, v10
	v_add_u32_e32 v28, v54, v3
	v_add_u32_e32 v30, v55, v10
	v_add_u32_e32 v32, v56, v3
	v_add_u32_e32 v34, v57, v10
	v_add_u32_e32 v36, v58, v3
	v_add_u32_e32 v38, v59, v10
	v_add_u32_e32 v40, v60, v3
	v_add_u32_e32 v42, v61, v10
	v_add_u32_e32 v44, v62, v3
	v_add_u32_e32 v46, v63, v10
	v_add_u32_e32 v48, v64, v3
	v_add_u32_e32 v50, v65, v10
	v_ashrrev_i32_e32 v15, 31, v14
	v_lshlrev_b64 v[16:17], 15, v[16:17]
	v_ashrrev_i32_e32 v27, 31, v26
	v_ashrrev_i32_e32 v25, 31, v24
	v_ashrrev_i32_e32 v31, 31, v30
	v_ashrrev_i32_e32 v29, 31, v28
	v_ashrrev_i32_e32 v35, 31, v34
	v_ashrrev_i32_e32 v33, 31, v32
	v_ashrrev_i32_e32 v39, 31, v38
	v_ashrrev_i32_e32 v37, 31, v36
	v_ashrrev_i32_e32 v43, 31, v42
	v_ashrrev_i32_e32 v41, 31, v40
	v_ashrrev_i32_e32 v47, 31, v46
	v_ashrrev_i32_e32 v45, 31, v44
	v_ashrrev_i32_e32 v51, 31, v50
	v_ashrrev_i32_e32 v49, 31, v48
	v_lshlrev_b64 v[14:15], 15, v[14:15]
	v_lshl_add_u64 v[16:17], v[12:13], 0, v[16:17]
	v_lshlrev_b64 v[24:25], 15, v[24:25]
	v_lshlrev_b64 v[26:27], 15, v[26:27]
	v_lshlrev_b64 v[28:29], 15, v[28:29]
	v_lshlrev_b64 v[30:31], 15, v[30:31]
	v_lshlrev_b64 v[32:33], 15, v[32:33]
	v_lshlrev_b64 v[34:35], 15, v[34:35]
	v_lshlrev_b64 v[36:37], 15, v[36:37]
	v_lshlrev_b64 v[38:39], 15, v[38:39]
	v_lshlrev_b64 v[40:41], 15, v[40:41]
	v_lshlrev_b64 v[42:43], 15, v[42:43]
	v_lshlrev_b64 v[44:45], 15, v[44:45]
	v_lshlrev_b64 v[46:47], 15, v[46:47]
	v_lshlrev_b64 v[48:49], 15, v[48:49]
	v_lshlrev_b64 v[50:51], 15, v[50:51]
	v_lshl_add_u64 v[14:15], v[12:13], 0, v[14:15]
	v_lshl_add_u64 v[26:27], v[12:13], 0, v[26:27]
	v_lshl_add_u64 v[24:25], v[12:13], 0, v[24:25]
	v_lshl_add_u64 v[30:31], v[12:13], 0, v[30:31]
	v_lshl_add_u64 v[28:29], v[12:13], 0, v[28:29]
	v_lshl_add_u64 v[34:35], v[12:13], 0, v[34:35]
	v_lshl_add_u64 v[32:33], v[12:13], 0, v[32:33]
	v_lshl_add_u64 v[38:39], v[12:13], 0, v[38:39]
	v_lshl_add_u64 v[36:37], v[12:13], 0, v[36:37]
	v_lshl_add_u64 v[42:43], v[12:13], 0, v[42:43]
	v_lshl_add_u64 v[40:41], v[12:13], 0, v[40:41]
	v_lshl_add_u64 v[46:47], v[12:13], 0, v[46:47]
	v_lshl_add_u64 v[44:45], v[12:13], 0, v[44:45]
	v_lshl_add_u64 v[50:51], v[12:13], 0, v[50:51]
	v_lshl_add_u64 v[48:49], v[12:13], 0, v[48:49]
	global_load_dword v66, v[16:17], off nt
	global_load_dword v67, v[14:15], off nt
	global_load_dword v68, v[26:27], off nt
	global_load_dword v69, v[24:25], off nt
	global_load_dword v70, v[30:31], off nt
	global_load_dword v71, v[28:29], off nt
	global_load_dword v72, v[34:35], off nt
	global_load_dword v73, v[32:33], off nt
	global_load_dword v74, v[38:39], off nt
	global_load_dword v75, v[36:37], off nt
	global_load_dword v76, v[42:43], off nt
	global_load_dword v77, v[40:41], off nt
	global_load_dword v78, v[46:47], off nt
	global_load_dword v79, v[44:45], off nt
	global_load_dword v80, v[50:51], off nt
	global_load_dword v81, v[48:49], off nt
	s_add_i32 s11, s11, 16
	s_add_i32 s15, s15, 16
	s_add_i32 s14, s14, -16
	v_mad_u64_u32 v[14:15], s[16:17], v11, s8, v[2:3]
	s_cmp_lg_u32 s14, 0
	v_mad_u64_u32 v[16:17], s[16:17], v7, s8, v[2:3]
	v_mad_u64_u32 v[24:25], s[16:17], v53, s8, v[2:3]
	v_mad_u64_u32 v[26:27], s[16:17], v52, s8, v[2:3]
	v_mad_u64_u32 v[28:29], s[16:17], v55, s8, v[2:3]
	v_mad_u64_u32 v[30:31], s[16:17], v54, s8, v[2:3]
	v_mad_u64_u32 v[32:33], s[16:17], v57, s8, v[2:3]
	v_mad_u64_u32 v[34:35], s[16:17], v56, s8, v[2:3]
	v_mad_u64_u32 v[36:37], s[16:17], v59, s8, v[2:3]
	v_mad_u64_u32 v[38:39], s[16:17], v58, s8, v[2:3]
	v_mad_u64_u32 v[40:41], s[16:17], v61, s8, v[2:3]
	v_mad_u64_u32 v[42:43], s[16:17], v60, s8, v[2:3]
	v_mad_u64_u32 v[44:45], s[16:17], v63, s8, v[2:3]
	v_mad_u64_u32 v[46:47], s[16:17], v62, s8, v[2:3]
	v_mad_u64_u32 v[48:49], s[16:17], v65, s8, v[2:3]
	v_mad_u64_u32 v[50:51], s[16:17], v64, s8, v[2:3]
	s_waitcnt vmcnt(15)
	ds_write_b32 v14, v66
	s_waitcnt vmcnt(14)
	ds_write_b32 v16, v67
	s_waitcnt vmcnt(13)
	ds_write_b32 v24, v68
	s_waitcnt vmcnt(12)
	ds_write_b32 v26, v69
	s_waitcnt vmcnt(11)
	ds_write_b32 v28, v70
	s_waitcnt vmcnt(10)
	ds_write_b32 v30, v71
	s_waitcnt vmcnt(9)
	ds_write_b32 v32, v72
	s_waitcnt vmcnt(8)
	ds_write_b32 v34, v73
	s_waitcnt vmcnt(7)
	ds_write_b32 v36, v74
	s_waitcnt vmcnt(6)
	ds_write_b32 v38, v75
	s_waitcnt vmcnt(5)
	ds_write_b32 v40, v76
	s_waitcnt vmcnt(4)
	ds_write_b32 v42, v77
	s_waitcnt vmcnt(3)
	ds_write_b32 v44, v78
	s_waitcnt vmcnt(2)
	ds_write_b32 v46, v79
	s_waitcnt vmcnt(1)
	ds_write_b32 v48, v80
	s_waitcnt vmcnt(0)
	ds_write_b32 v50, v81
	s_cbranch_scc1 .LBB0_279
; #define LAS __attribute__((address_space(3)))
;     __device__ __forceinline__ const float* in(int i) const { return (const float*)(const __attribute__((address_space(1))) float*)ld(i); }
; __device__ __forceinline__ unsigned pk2(float lo, float hi) { unsigned r; asm("v_cvt_pk_bf16_f32 %0, %1, %2" : "=v"(r) : "v"(lo), "v"(hi)); return r; }
; __device__ __forceinline__ void transpose_item(const float* W, int ldw, bf16_t* WT, int ldo, LAS float* scr, int k0, int n0, int lane, const float* rs = nullptr) {
;     ...
;     const int c = lane & 7;
; #pragma unroll
;     for (int j = 0; j < 4; ++j) { const int n = (lane >> 3) + 8 * j; const LAS float* s = scr + (8 * c) * 33 + n; const float m = rs ? rs[n0 + n] : 1.f;
;         u32x4 o; o.x = pk2(s[0 * 33] * m, s[1 * 33] * m); o.y = pk2(s[2 * 33] * m, s[3 * 33] * m); o.z = pk2(s[4 * 33] * m, s[5 * 33] * m); o.w = pk2(s[6 * 33] * m, s[7 * 33] * m);
;         *(u32x4*)(WT + (size_t)(n0 + n) * ldo + k0 + 8 * c) = o; }
;     asm volatile("s_waitcnt lgkmcnt(0)" ::: "memory");
; __device__ __forceinline__ void convert_sub(const DArgs& a, LAS unsigned char* lds, int which, int c0) {
;     ...
;     case CV_FF1_0: transpose_matrix(a.in(I_WFF1), D, DFF, (bf16_t*)(w + W_FF1T), D, scr, gw, ngw, lane); break;
	s_waitcnt lgkmcnt(0)
	ds_read2_b32 v[24:25], v19 offset0:33 offset1:41
	ds_read2_b32 v[26:27], v19 offset1:8
	ds_read2_b32 v[28:29], v19 offset0:66 offset1:74
	ds_read2_b32 v[30:31], v19 offset0:99 offset1:107
	ds_read2_b32 v[32:33], v19 offset0:132 offset1:140
	ds_read2_b32 v[34:35], v19 offset0:165 offset1:173
	ds_read2_b32 v[36:37], v19 offset0:198 offset1:206
	ds_read2_b32 v[38:39], v19 offset0:231 offset1:239
	v_or_b32_e32 v16, v6, v18
	v_ashrrev_i32_e32 v11, 31, v10
	v_ashrrev_i32_e32 v17, 31, v16
	v_lshl_add_u64 v[14:15], v[10:11], 1, v[4:5]
	v_lshlrev_b64 v[16:17], 12, v[16:17]
	v_lshl_add_u64 v[16:17], v[14:15], 0, v[16:17]
	s_waitcnt lgkmcnt(6)
	v_cvt_pk_bf16_f32 v10, v26, v24
	s_waitcnt lgkmcnt(4)
	v_cvt_pk_bf16_f32 v11, v28, v30
	s_waitcnt lgkmcnt(2)
	v_cvt_pk_bf16_f32 v12, v32, v34
	s_waitcnt lgkmcnt(0)
	v_cvt_pk_bf16_f32 v13, v36, v38
	global_store_dwordx4 v[16:17], v[10:13], off
	v_or_b32_e32 v16, v6, v20
	v_ashrrev_i32_e32 v17, 31, v16
	v_lshlrev_b64 v[16:17], 12, v[16:17]
	v_lshl_add_u64 v[16:17], v[14:15], 0, v[16:17]
	v_cvt_pk_bf16_f32 v10, v27, v25
	v_cvt_pk_bf16_f32 v11, v29, v31
	v_cvt_pk_bf16_f32 v12, v33, v35
	v_cvt_pk_bf16_f32 v13, v37, v39
	global_store_dwordx4 v[16:17], v[10:13], off
	ds_read2_b32 v[24:25], v19 offset0:16 offset1:24
	ds_read2_b32 v[26:27], v19 offset0:49 offset1:57
	ds_read2_b32 v[28:29], v19 offset0:82 offset1:90
	ds_read2_b32 v[30:31], v19 offset0:115 offset1:123
	ds_read2_b32 v[32:33], v19 offset0:148 offset1:156
	ds_read2_b32 v[34:35], v19 offset0:181 offset1:189
	ds_read2_b32 v[36:37], v19 offset0:214 offset1:222
	ds_read2_b32 v[38:39], v19 offset0:247 offset1:255
	v_or_b32_e32 v16, v6, v21
	v_or_b32_e32 v6, v6, v22
	v_ashrrev_i32_e32 v17, 31, v16
	v_ashrrev_i32_e32 v7, 31, v6
	v_lshlrev_b64 v[16:17], 12, v[16:17]
	v_lshlrev_b64 v[6:7], 12, v[6:7]
	s_waitcnt lgkmcnt(6)
	v_cvt_pk_bf16_f32 v10, v24, v26
	s_waitcnt lgkmcnt(4)
	v_cvt_pk_bf16_f32 v11, v28, v30
	s_waitcnt lgkmcnt(2)
	v_cvt_pk_bf16_f32 v12, v32, v34
	s_waitcnt lgkmcnt(0)
	v_cvt_pk_bf16_f32 v13, v36, v38
	v_lshl_add_u64 v[16:17], v[14:15], 0, v[16:17]
	v_lshl_add_u64 v[6:7], v[14:15], 0, v[6:7]
	global_store_dwordx4 v[16:17], v[10:13], off
	v_add_u32_e32 v23, s10, v23
	v_cmp_lt_i32_e32 vcc, s9, v23
	v_cvt_pk_bf16_f32 v10, v25, v27
	v_cvt_pk_bf16_f32 v11, v29, v31
	v_cvt_pk_bf16_f32 v12, v33, v35
	v_cvt_pk_bf16_f32 v13, v37, v39
	global_store_dwordx4 v[6:7], v[10:13], off
	s_waitcnt lgkmcnt(0)
	s_or_b64 s[6:7], vcc, s[6:7]
	s_andn2_b64 exec, exec, s[6:7]
	s_cbranch_execnz .LBB0_278

; #define LAS __attribute__((address_space(3)))
;     __device__ __forceinline__ const float* in(int i) const { return (const float*)(const __attribute__((address_space(1))) float*)ld(i); }
; __device__ __forceinline__ void transpose_item(const float* W, int ldw, bf16_t* WT, int ldo, LAS float* scr, int k0, int n0, int lane, const float* rs = nullptr) {
; #pragma unroll 8
;     for (int i = 0; i < 32; ++i) { const int kk = 2 * i + (lane >> 5); scr[kk * 33 + (lane & 31)] = W[(size_t)(k0 + kk) * ldw + n0 + (lane & 31)]; }
;     asm volatile("s_waitcnt lgkmcnt(0)" ::: "memory");
; __device__ __forceinline__ void convert_sub(const DArgs& a, LAS unsigned char* lds, int which, int c0) {
;     ...
;     case CV_FF2_0: transpose_matrix(a.in(I_WFF2), DFF, D, (bf16_t*)(w + W_FF2T), DFF, scr, gw, ngw, lane); break;
.LBB0_958:
	s_lshl_b32 s16, s15, 1
	s_lshl_b32 s17, s9, 1
	v_or_b32_e32 v7, s16, v1
	v_or_b32_e32 v13, s17, v0
	s_add_i32 s18, s16, 4
	s_add_i32 s19, s17, 4
	s_add_i32 s20, s16, 8
	s_add_i32 s21, s17, 8
	s_add_i32 s22, s16, 12
	s_add_i32 s23, s17, 12
	s_add_i32 s24, s16, 16
	s_add_i32 s25, s17, 16
	s_add_i32 s26, s16, 20
	s_add_i32 s27, s17, 20
	s_add_i32 s28, s16, 24
	s_add_i32 s29, s17, 24
	s_add_i32 s16, s16, 28
	s_add_i32 s17, s17, 28
	v_add_u32_e32 v26, v13, v14
	v_or_b32_e32 v15, s18, v1
	v_or_b32_e32 v56, s19, v0
	v_or_b32_e32 v57, s20, v1
	v_or_b32_e32 v58, s21, v0
	v_or_b32_e32 v59, s22, v1
	v_or_b32_e32 v60, s23, v0
	v_or_b32_e32 v61, s24, v1
	v_or_b32_e32 v62, s25, v0
	v_or_b32_e32 v63, s26, v1
	v_or_b32_e32 v64, s27, v0
	v_or_b32_e32 v65, s28, v1
	v_or_b32_e32 v66, s29, v0
	v_or_b32_e32 v67, s16, v1
	v_or_b32_e32 v68, s17, v0
	v_add_u32_e32 v24, v7, v3
	v_ashrrev_i32_e32 v27, 31, v26
	v_add_u32_e32 v28, v15, v3
	v_add_u32_e32 v30, v56, v14
	v_add_u32_e32 v32, v57, v3
	v_add_u32_e32 v34, v58, v14
	v_add_u32_e32 v36, v59, v3
	v_add_u32_e32 v38, v60, v14
	v_add_u32_e32 v40, v61, v3
	v_add_u32_e32 v42, v62, v14
	v_add_u32_e32 v44, v63, v3
	v_add_u32_e32 v46, v64, v14
	v_add_u32_e32 v48, v65, v3
	v_add_u32_e32 v50, v66, v14
	v_add_u32_e32 v52, v67, v3
	v_add_u32_e32 v54, v68, v14
	v_ashrrev_i32_e32 v25, 31, v24
	v_lshlrev_b64 v[26:27], 13, v[26:27]
	v_ashrrev_i32_e32 v31, 31, v30
	v_ashrrev_i32_e32 v29, 31, v28
	v_ashrrev_i32_e32 v35, 31, v34
	v_ashrrev_i32_e32 v33, 31, v32
	v_ashrrev_i32_e32 v39, 31, v38
	v_ashrrev_i32_e32 v37, 31, v36
	v_ashrrev_i32_e32 v43, 31, v42
	v_ashrrev_i32_e32 v41, 31, v40
	v_ashrrev_i32_e32 v47, 31, v46
	v_ashrrev_i32_e32 v45, 31, v44
	v_ashrrev_i32_e32 v51, 31, v50
	v_ashrrev_i32_e32 v49, 31, v48
	v_ashrrev_i32_e32 v55, 31, v54
	v_ashrrev_i32_e32 v53, 31, v52
	v_lshlrev_b64 v[24:25], 13, v[24:25]
	v_lshl_add_u64 v[26:27], v[16:17], 0, v[26:27]
	v_lshlrev_b64 v[28:29], 13, v[28:29]
	v_lshlrev_b64 v[30:31], 13, v[30:31]
	v_lshlrev_b64 v[32:33], 13, v[32:33]
	v_lshlrev_b64 v[34:35], 13, v[34:35]
	v_lshlrev_b64 v[36:37], 13, v[36:37]
	v_lshlrev_b64 v[38:39], 13, v[38:39]
	v_lshlrev_b64 v[40:41], 13, v[40:41]
	v_lshlrev_b64 v[42:43], 13, v[42:43]
	v_lshlrev_b64 v[44:45], 13, v[44:45]
	v_lshlrev_b64 v[46:47], 13, v[46:47]
	v_lshlrev_b64 v[48:49], 13, v[48:49]
	v_lshlrev_b64 v[50:51], 13, v[50:51]
	v_lshlrev_b64 v[52:53], 13, v[52:53]
	v_lshlrev_b64 v[54:55], 13, v[54:55]
	v_lshl_add_u64 v[24:25], v[16:17], 0, v[24:25]
	v_lshl_add_u64 v[30:31], v[16:17], 0, v[30:31]
	v_lshl_add_u64 v[28:29], v[16:17], 0, v[28:29]
	v_lshl_add_u64 v[34:35], v[16:17], 0, v[34:35]
	v_lshl_add_u64 v[32:33], v[16:17], 0, v[32:33]
	v_lshl_add_u64 v[38:39], v[16:17], 0, v[38:39]
	v_lshl_add_u64 v[36:37], v[16:17], 0, v[36:37]
	v_lshl_add_u64 v[42:43], v[16:17], 0, v[42:43]
	v_lshl_add_u64 v[40:41], v[16:17], 0, v[40:41]
	v_lshl_add_u64 v[46:47], v[16:17], 0, v[46:47]
	v_lshl_add_u64 v[44:45], v[16:17], 0, v[44:45]
	v_lshl_add_u64 v[50:51], v[16:17], 0, v[50:51]
	v_lshl_add_u64 v[48:49], v[16:17], 0, v[48:49]
	v_lshl_add_u64 v[54:55], v[16:17], 0, v[54:55]
	v_lshl_add_u64 v[52:53], v[16:17], 0, v[52:53]
	global_load_dword v69, v[26:27], off nt
	global_load_dword v70, v[24:25], off nt
	global_load_dword v71, v[30:31], off nt
	global_load_dword v72, v[28:29], off nt
	global_load_dword v73, v[34:35], off nt
	global_load_dword v74, v[32:33], off nt
	global_load_dword v75, v[38:39], off nt
	global_load_dword v76, v[36:37], off nt
	global_load_dword v77, v[42:43], off nt
	global_load_dword v78, v[40:41], off nt
	global_load_dword v79, v[46:47], off nt
	global_load_dword v80, v[44:45], off nt
	global_load_dword v81, v[50:51], off nt
	global_load_dword v82, v[48:49], off nt
	global_load_dword v83, v[54:55], off nt
	global_load_dword v84, v[52:53], off nt
	s_add_i32 s9, s9, 16
	s_add_i32 s15, s15, 16
	s_add_i32 s14, s14, -16
	v_mad_u64_u32 v[24:25], s[16:17], v13, s11, v[2:3]
	s_cmp_lg_u32 s14, 0
	v_mad_u64_u32 v[26:27], s[16:17], v7, s11, v[2:3]
	v_mad_u64_u32 v[28:29], s[16:17], v56, s11, v[2:3]
	v_mad_u64_u32 v[30:31], s[16:17], v15, s11, v[2:3]
	v_mad_u64_u32 v[32:33], s[16:17], v58, s11, v[2:3]
	v_mad_u64_u32 v[34:35], s[16:17], v57, s11, v[2:3]
	v_mad_u64_u32 v[36:37], s[16:17], v60, s11, v[2:3]
	v_mad_u64_u32 v[38:39], s[16:17], v59, s11, v[2:3]
	v_mad_u64_u32 v[40:41], s[16:17], v62, s11, v[2:3]
	v_mad_u64_u32 v[42:43], s[16:17], v61, s11, v[2:3]
	v_mad_u64_u32 v[44:45], s[16:17], v64, s11, v[2:3]
	v_mad_u64_u32 v[46:47], s[16:17], v63, s11, v[2:3]
	v_mad_u64_u32 v[48:49], s[16:17], v66, s11, v[2:3]
	v_mad_u64_u32 v[50:51], s[16:17], v65, s11, v[2:3]
	v_mad_u64_u32 v[52:53], s[16:17], v68, s11, v[2:3]
	v_mad_u64_u32 v[54:55], s[16:17], v67, s11, v[2:3]
	s_waitcnt vmcnt(15)
	ds_write_b32 v24, v69
	s_waitcnt vmcnt(14)
	ds_write_b32 v26, v70
	s_waitcnt vmcnt(13)
	ds_write_b32 v28, v71
	s_waitcnt vmcnt(12)
	ds_write_b32 v30, v72
	s_waitcnt vmcnt(11)
	ds_write_b32 v32, v73
	s_waitcnt vmcnt(10)
	ds_write_b32 v34, v74
	s_waitcnt vmcnt(9)
	ds_write_b32 v36, v75
	s_waitcnt vmcnt(8)
	ds_write_b32 v38, v76
	s_waitcnt vmcnt(7)
	ds_write_b32 v40, v77
	s_waitcnt vmcnt(6)
	ds_write_b32 v42, v78
	s_waitcnt vmcnt(5)
	ds_write_b32 v44, v79
	s_waitcnt vmcnt(4)
	ds_write_b32 v46, v80
	s_waitcnt vmcnt(3)
	ds_write_b32 v48, v81
	s_waitcnt vmcnt(2)
	ds_write_b32 v50, v82
	s_waitcnt vmcnt(1)
	ds_write_b32 v52, v83
	s_waitcnt vmcnt(0)
	ds_write_b32 v54, v84
	s_cbranch_scc1 .LBB0_958
; #define LAS __attribute__((address_space(3)))
;     __device__ __forceinline__ const float* in(int i) const { return (const float*)(const __attribute__((address_space(1))) float*)ld(i); }
; __device__ __forceinline__ unsigned pk2(float lo, float hi) { unsigned r; asm("v_cvt_pk_bf16_f32 %0, %1, %2" : "=v"(r) : "v"(lo), "v"(hi)); return r; }
; __device__ __forceinline__ void transpose_item(const float* W, int ldw, bf16_t* WT, int ldo, LAS float* scr, int k0, int n0, int lane, const float* rs = nullptr) {
;     ...
;     const int c = lane & 7;
; #pragma unroll
;     for (int j = 0; j < 4; ++j) { const int n = (lane >> 3) + 8 * j; const LAS float* s = scr + (8 * c) * 33 + n; const float m = rs ? rs[n0 + n] : 1.f;
;         u32x4 o; o.x = pk2(s[0 * 33] * m, s[1 * 33] * m); o.y = pk2(s[2 * 33] * m, s[3 * 33] * m); o.z = pk2(s[4 * 33] * m, s[5 * 33] * m); o.w = pk2(s[6 * 33] * m, s[7 * 33] * m);
;         *(u32x4*)(WT + (size_t)(n0 + n) * ldo + k0 + 8 * c) = o; }
;     asm volatile("s_waitcnt lgkmcnt(0)" ::: "memory");
; __device__ __forceinline__ void convert_sub(const DArgs& a, LAS unsigned char* lds, int which, int c0) {
;     ...
;     case CV_FF2_0: transpose_matrix(a.in(I_WFF2), DFF, D, (bf16_t*)(w + W_FF2T), DFF, scr, gw, ngw, lane); break;
	s_waitcnt lgkmcnt(0)
	ds_read2_b32 v[28:29], v19 offset0:33 offset1:41
	ds_read2_b32 v[30:31], v19 offset1:8
	ds_read2_b32 v[32:33], v19 offset0:66 offset1:74
	ds_read2_b32 v[34:35], v19 offset0:99 offset1:107
	ds_read2_b32 v[36:37], v19 offset0:132 offset1:140
	ds_read2_b32 v[38:39], v19 offset0:165 offset1:173
	ds_read2_b32 v[40:41], v19 offset0:198 offset1:206
	ds_read2_b32 v[42:43], v19 offset0:231 offset1:239
	v_or_b32_e32 v26, v12, v18
	v_ashrrev_i32_e32 v15, 31, v14
	v_ashrrev_i32_e32 v27, 31, v26
	v_lshl_add_u64 v[24:25], v[14:15], 1, v[10:11]
	v_lshlrev_b64 v[26:27], 14, v[26:27]
	v_lshl_add_u64 v[26:27], v[24:25], 0, v[26:27]
	s_waitcnt lgkmcnt(6)
	v_cvt_pk_bf16_f32 v14, v30, v28
	s_waitcnt lgkmcnt(4)
	v_cvt_pk_bf16_f32 v15, v32, v34
	s_waitcnt lgkmcnt(2)
	v_cvt_pk_bf16_f32 v16, v36, v38
	s_waitcnt lgkmcnt(0)
	v_cvt_pk_bf16_f32 v17, v40, v42
	global_store_dwordx4 v[26:27], v[14:17], off
	v_or_b32_e32 v26, v12, v20
	v_ashrrev_i32_e32 v27, 31, v26
	v_lshlrev_b64 v[26:27], 14, v[26:27]
	v_lshl_add_u64 v[26:27], v[24:25], 0, v[26:27]
	v_cvt_pk_bf16_f32 v14, v31, v29
	v_cvt_pk_bf16_f32 v15, v33, v35
	v_cvt_pk_bf16_f32 v16, v37, v39
	v_cvt_pk_bf16_f32 v17, v41, v43
	global_store_dwordx4 v[26:27], v[14:17], off
	ds_read2_b32 v[28:29], v19 offset0:16 offset1:24
	ds_read2_b32 v[30:31], v19 offset0:49 offset1:57
	ds_read2_b32 v[32:33], v19 offset0:82 offset1:90
	ds_read2_b32 v[34:35], v19 offset0:115 offset1:123
	ds_read2_b32 v[36:37], v19 offset0:148 offset1:156
	ds_read2_b32 v[38:39], v19 offset0:181 offset1:189
	ds_read2_b32 v[40:41], v19 offset0:214 offset1:222
	ds_read2_b32 v[42:43], v19 offset0:247 offset1:255
	v_or_b32_e32 v26, v12, v21
	v_ashrrev_i32_e32 v27, 31, v26
	v_lshlrev_b64 v[26:27], 14, v[26:27]
	s_waitcnt lgkmcnt(2)
	v_cvt_pk_bf16_f32 v16, v36, v38
	v_lshl_add_u64 v[26:27], v[24:25], 0, v[26:27]
	v_cvt_pk_bf16_f32 v14, v28, v30
	v_cvt_pk_bf16_f32 v15, v32, v34
	s_waitcnt lgkmcnt(0)
	v_cvt_pk_bf16_f32 v17, v40, v42
	global_store_dwordx4 v[26:27], v[14:17], off
	v_cvt_pk_bf16_f32 v13, v33, v35
	v_add_u32_e32 v5, s10, v5
	v_cmp_lt_i32_e32 vcc, s8, v5
	v_or_b32_e32 v16, v12, v22
	v_ashrrev_i32_e32 v17, 31, v16
	v_lshlrev_b64 v[16:17], 14, v[16:17]
	v_lshl_add_u64 v[16:17], v[24:25], 0, v[16:17]
	v_cvt_pk_bf16_f32 v12, v29, v31
	v_cvt_pk_bf16_f32 v14, v37, v39
	v_cvt_pk_bf16_f32 v15, v41, v43
	global_store_dwordx4 v[16:17], v[12:15], off
	s_waitcnt lgkmcnt(0)
	s_or_b64 s[6:7], vcc, s[6:7]
	s_andn2_b64 exec, exec, s[6:7]
	s_cbranch_execnz .LBB0_957
	s_or_b64 exec, exec, s[6:7]
	s_add_i32 s6, 0, 0x20108
	v_mov_b32_e32 v1, s6
	ds_read_b64 v[8:9], v1

; #define LAS __attribute__((address_space(3)))
;     __device__ __forceinline__ const float* in(int i) const { return (const float*)(const __attribute__((address_space(1))) float*)ld(i); }
; __device__ __forceinline__ unsigned pk2(float lo, float hi) { unsigned r; asm("v_cvt_pk_bf16_f32 %0, %1, %2" : "=v"(r) : "v"(lo), "v"(hi)); return r; }
; __device__ __forceinline__ void transpose_item(const float* W, int ldw, bf16_t* WT, int ldo, LAS float* scr, int k0, int n0, int lane, const float* rs = nullptr) {
; #pragma unroll 8
;     for (int i = 0; i < 32; ++i) { const int kk = 2 * i + (lane >> 5); scr[kk * 33 + (lane & 31)] = W[(size_t)(k0 + kk) * ldw + n0 + (lane & 31)]; }
;     asm volatile("s_waitcnt lgkmcnt(0)" ::: "memory");
;     const int c = lane & 7;
; #pragma unroll
;     for (int j = 0; j < 4; ++j) { const int n = (lane >> 3) + 8 * j; const LAS float* s = scr + (8 * c) * 33 + n; const float m = rs ? rs[n0 + n] : 1.f;
;         u32x4 o; o.x = pk2(s[0 * 33] * m, s[1 * 33] * m); o.y = pk2(s[2 * 33] * m, s[3 * 33] * m); o.z = pk2(s[4 * 33] * m, s[5 * 33] * m); o.w = pk2(s[6 * 33] * m, s[7 * 33] * m);
;         *(u32x4*)(WT + (size_t)(n0 + n) * ldo + k0 + 8 * c) = o; }
;     asm volatile("s_waitcnt lgkmcnt(0)" ::: "memory");
; __device__ __forceinline__ void convert_sub(const DArgs& a, LAS unsigned char* lds, int which, int c0) {
;     ...
;     case CV_QKV: transpose_matrix(a.in(I_WQKV), D, 3 * D, (bf16_t*)(w + W_QKVT), D, scr, gw, ngw, lane); break;
.LBB0_964:
	s_lshl_b32 s19, s18, 1
	s_lshl_b32 s20, s16, 1
	v_or_b32_e32 v7, s19, v1
	v_or_b32_e32 v11, s20, v0
	s_add_i32 s21, s19, 4
	s_add_i32 s22, s20, 4
	s_add_i32 s23, s19, 8
	s_add_i32 s24, s20, 8
	s_add_i32 s25, s19, 12
	s_add_i32 s26, s20, 12
	s_add_i32 s27, s19, 16
	s_add_i32 s28, s20, 16
	s_add_i32 s29, s19, 20
	s_add_i32 s30, s20, 20
	s_add_i32 s31, s19, 24
	s_add_i32 s33, s20, 24
	s_add_i32 s19, s19, 28
	s_add_i32 s20, s20, 28
	v_add_u32_e32 v14, v11, v10
	v_or_b32_e32 v52, s21, v1
	v_or_b32_e32 v53, s22, v0
	v_or_b32_e32 v54, s23, v1
	v_or_b32_e32 v55, s24, v0
	v_or_b32_e32 v56, s25, v1
	v_or_b32_e32 v57, s26, v0
	v_or_b32_e32 v58, s27, v1
	v_or_b32_e32 v59, s28, v0
	v_or_b32_e32 v60, s29, v1
	v_or_b32_e32 v61, s30, v0
	v_or_b32_e32 v62, s31, v1
	v_or_b32_e32 v63, s33, v0
	v_or_b32_e32 v64, s19, v1
	v_or_b32_e32 v65, s20, v0
	v_add_u32_e32 v16, v7, v3
	v_mad_i64_i32 v[14:15], s[20:21], v14, s11, v[12:13]
	v_add_u32_e32 v26, v52, v3
	v_add_u32_e32 v24, v53, v10
	v_add_u32_e32 v30, v54, v3
	v_add_u32_e32 v28, v55, v10
	v_add_u32_e32 v34, v56, v3
	v_add_u32_e32 v32, v57, v10
	v_add_u32_e32 v38, v58, v3
	v_add_u32_e32 v36, v59, v10
	v_add_u32_e32 v42, v60, v3
	v_add_u32_e32 v40, v61, v10
	v_add_u32_e32 v46, v62, v3
	v_add_u32_e32 v44, v63, v10
	v_add_u32_e32 v50, v64, v3
	v_add_u32_e32 v48, v65, v10
	v_mad_i64_i32 v[16:17], s[20:21], v16, s11, v[12:13]
	v_mad_i64_i32 v[24:25], s[20:21], v24, s11, v[12:13]
	v_mad_i64_i32 v[26:27], s[20:21], v26, s11, v[12:13]
	v_mad_i64_i32 v[28:29], s[20:21], v28, s11, v[12:13]
	v_mad_i64_i32 v[30:31], s[20:21], v30, s11, v[12:13]
	v_mad_i64_i32 v[32:33], s[20:21], v32, s11, v[12:13]
	v_mad_i64_i32 v[34:35], s[20:21], v34, s11, v[12:13]
	v_mad_i64_i32 v[36:37], s[20:21], v36, s11, v[12:13]
	v_mad_i64_i32 v[38:39], s[20:21], v38, s11, v[12:13]
	v_mad_i64_i32 v[40:41], s[20:21], v40, s11, v[12:13]
	v_mad_i64_i32 v[42:43], s[20:21], v42, s11, v[12:13]
	v_mad_i64_i32 v[44:45], s[20:21], v44, s11, v[12:13]
	v_mad_i64_i32 v[46:47], s[20:21], v46, s11, v[12:13]
	v_mad_i64_i32 v[48:49], s[20:21], v48, s11, v[12:13]
	v_mad_i64_i32 v[50:51], s[20:21], v50, s11, v[12:13]
	global_load_dword v66, v[14:15], off nt
	global_load_dword v67, v[16:17], off nt
	global_load_dword v68, v[24:25], off nt
	global_load_dword v69, v[26:27], off nt
	global_load_dword v70, v[28:29], off nt
	global_load_dword v71, v[30:31], off nt
	global_load_dword v72, v[32:33], off nt
	global_load_dword v73, v[34:35], off nt
	global_load_dword v74, v[36:37], off nt
	global_load_dword v75, v[38:39], off nt
	global_load_dword v76, v[40:41], off nt
	global_load_dword v77, v[42:43], off nt
	global_load_dword v78, v[44:45], off nt
	global_load_dword v79, v[46:47], off nt
	global_load_dword v80, v[48:49], off nt
	global_load_dword v81, v[50:51], off nt
	s_add_i32 s16, s16, 16
	s_add_i32 s18, s18, 16
	s_add_i32 s17, s17, -16
	v_mad_u64_u32 v[14:15], s[20:21], v11, s14, v[2:3]
	s_cmp_lg_u32 s17, 0
	v_mad_u64_u32 v[16:17], s[20:21], v7, s14, v[2:3]
	v_mad_u64_u32 v[24:25], s[20:21], v53, s14, v[2:3]
	v_mad_u64_u32 v[26:27], s[20:21], v52, s14, v[2:3]
	v_mad_u64_u32 v[28:29], s[20:21], v55, s14, v[2:3]
	v_mad_u64_u32 v[30:31], s[20:21], v54, s14, v[2:3]
	v_mad_u64_u32 v[32:33], s[20:21], v57, s14, v[2:3]
	v_mad_u64_u32 v[34:35], s[20:21], v56, s14, v[2:3]
	v_mad_u64_u32 v[36:37], s[20:21], v59, s14, v[2:3]
	v_mad_u64_u32 v[38:39], s[20:21], v58, s14, v[2:3]
	v_mad_u64_u32 v[40:41], s[20:21], v61, s14, v[2:3]
	v_mad_u64_u32 v[42:43], s[20:21], v60, s14, v[2:3]
	v_mad_u64_u32 v[44:45], s[20:21], v63, s14, v[2:3]
	v_mad_u64_u32 v[46:47], s[20:21], v62, s14, v[2:3]
	v_mad_u64_u32 v[48:49], s[20:21], v65, s14, v[2:3]
	v_mad_u64_u32 v[50:51], s[20:21], v64, s14, v[2:3]
	s_waitcnt vmcnt(15)
	ds_write_b32 v14, v66
	s_waitcnt vmcnt(14)
	ds_write_b32 v16, v67
	s_waitcnt vmcnt(13)
	ds_write_b32 v24, v68
	s_waitcnt vmcnt(12)
	ds_write_b32 v26, v69
	s_waitcnt vmcnt(11)
	ds_write_b32 v28, v70
	s_waitcnt vmcnt(10)
	ds_write_b32 v30, v71
	s_waitcnt vmcnt(9)
	ds_write_b32 v32, v72
	s_waitcnt vmcnt(8)
	ds_write_b32 v34, v73
	s_waitcnt vmcnt(7)
	ds_write_b32 v36, v74
	s_waitcnt vmcnt(6)
	ds_write_b32 v38, v75
	s_waitcnt vmcnt(5)
	ds_write_b32 v40, v76
	s_waitcnt vmcnt(4)
	ds_write_b32 v42, v77
	s_waitcnt vmcnt(3)
	ds_write_b32 v44, v78
	s_waitcnt vmcnt(2)
	ds_write_b32 v46, v79
	s_waitcnt vmcnt(1)
	ds_write_b32 v48, v80
	s_waitcnt vmcnt(0)
	ds_write_b32 v50, v81
	s_cbranch_scc1 .LBB0_964
	s_waitcnt lgkmcnt(0)
	ds_read2_b32 v[24:25], v19 offset0:33 offset1:41
	ds_read2_b32 v[26:27], v19 offset1:8
	ds_read2_b32 v[28:29], v19 offset0:66 offset1:74
	ds_read2_b32 v[30:31], v19 offset0:99 offset1:107
	ds_read2_b32 v[32:33], v19 offset0:132 offset1:140
	ds_read2_b32 v[34:35], v19 offset0:165 offset1:173
	ds_read2_b32 v[36:37], v19 offset0:198 offset1:206
	ds_read2_b32 v[38:39], v19 offset0:231 offset1:239
	v_or_b32_e32 v16, v6, v18
	v_ashrrev_i32_e32 v11, 31, v10
	v_ashrrev_i32_e32 v17, 31, v16
	v_lshl_add_u64 v[14:15], v[10:11], 1, v[4:5]
	v_lshlrev_b64 v[16:17], 12, v[16:17]
	v_lshl_add_u64 v[16:17], v[14:15], 0, v[16:17]
	s_waitcnt lgkmcnt(6)
	v_cvt_pk_bf16_f32 v10, v26, v24
	s_waitcnt lgkmcnt(4)
	v_cvt_pk_bf16_f32 v11, v28, v30
	s_waitcnt lgkmcnt(2)
	v_cvt_pk_bf16_f32 v12, v32, v34
	s_waitcnt lgkmcnt(0)
	v_cvt_pk_bf16_f32 v13, v36, v38
	global_store_dwordx4 v[16:17], v[10:13], off
	v_or_b32_e32 v16, v6, v20
	v_ashrrev_i32_e32 v17, 31, v16
	v_lshlrev_b64 v[16:17], 12, v[16:17]
	v_lshl_add_u64 v[16:17], v[14:15], 0, v[16:17]
	v_cvt_pk_bf16_f32 v10, v27, v25
	v_cvt_pk_bf16_f32 v11, v29, v31
	v_cvt_pk_bf16_f32 v12, v33, v35
	v_cvt_pk_bf16_f32 v13, v37, v39
	global_store_dwordx4 v[16:17], v[10:13], off
	ds_read2_b32 v[24:25], v19 offset0:16 offset1:24
	ds_read2_b32 v[26:27], v19 offset0:49 offset1:57
	ds_read2_b32 v[28:29], v19 offset0:82 offset1:90
	ds_read2_b32 v[30:31], v19 offset0:115 offset1:123
	ds_read2_b32 v[32:33], v19 offset0:148 offset1:156
	ds_read2_b32 v[34:35], v19 offset0:181 offset1:189
	ds_read2_b32 v[36:37], v19 offset0:214 offset1:222
	ds_read2_b32 v[38:39], v19 offset0:247 offset1:255
	v_or_b32_e32 v16, v6, v21
	v_or_b32_e32 v6, v6, v22
	v_ashrrev_i32_e32 v17, 31, v16
	v_ashrrev_i32_e32 v7, 31, v6
	v_lshlrev_b64 v[16:17], 12, v[16:17]
	v_lshlrev_b64 v[6:7], 12, v[6:7]
	s_waitcnt lgkmcnt(6)
	v_cvt_pk_bf16_f32 v10, v24, v26
	s_waitcnt lgkmcnt(4)
	v_cvt_pk_bf16_f32 v11, v28, v30
	s_waitcnt lgkmcnt(2)
	v_cvt_pk_bf16_f32 v12, v32, v34
	s_waitcnt lgkmcnt(0)
	v_cvt_pk_bf16_f32 v13, v36, v38
	v_lshl_add_u64 v[16:17], v[14:15], 0, v[16:17]
	v_lshl_add_u64 v[6:7], v[14:15], 0, v[6:7]
	global_store_dwordx4 v[16:17], v[10:13], off
	v_add_u32_e32 v23, s10, v23
	v_cmp_lt_i32_e32 vcc, s15, v23
	v_cvt_pk_bf16_f32 v10, v25, v27
	v_cvt_pk_bf16_f32 v11, v29, v31
	v_cvt_pk_bf16_f32 v12, v33, v35
	v_cvt_pk_bf16_f32 v13, v37, v39
	global_store_dwordx4 v[6:7], v[10:13], off
	s_waitcnt lgkmcnt(0)
	s_or_b64 s[6:7], vcc, s[6:7]
	s_andn2_b64 exec, exec, s[6:7]
	s_cbranch_execnz .LBB0_963

; #define LAS __attribute__((address_space(3)))
;     __device__ __forceinline__ const float* in(int i) const { return (const float*)(const __attribute__((address_space(1))) float*)ld(i); }
; __device__ __forceinline__ void transpose_item(const float* W, int ldw, bf16_t* WT, int ldo, LAS float* scr, int k0, int n0, int lane, const float* rs = nullptr) {
; #pragma unroll 8
;     for (int i = 0; i < 32; ++i) { const int kk = 2 * i + (lane >> 5); scr[kk * 33 + (lane & 31)] = W[(size_t)(k0 + kk) * ldw + n0 + (lane & 31)]; }
;     asm volatile("s_waitcnt lgkmcnt(0)" ::: "memory");
; __device__ __forceinline__ void convert_sub(const DArgs& a, LAS unsigned char* lds, int which, int c0) {
;     ...
;     case CV_OUT1: transpose_matrix(a.in(I_WOUT1), D, D, (bf16_t*)(w + W_OUT1T), D, scr, gw, ngw, lane); break;
.LBB0_1211:
	s_lshl_b32 s16, s15, 1
	s_lshl_b32 s17, s14, 1
	v_or_b32_e32 v7, s16, v1
	v_or_b32_e32 v13, s17, v0
	s_add_i32 s18, s16, 4
	s_add_i32 s19, s17, 4
	s_add_i32 s20, s16, 8
	s_add_i32 s21, s17, 8
	s_add_i32 s22, s16, 12
	s_add_i32 s23, s17, 12
	s_add_i32 s24, s16, 16
	s_add_i32 s25, s17, 16
	s_add_i32 s26, s16, 20
	s_add_i32 s27, s17, 20
	s_add_i32 s28, s16, 24
	s_add_i32 s29, s17, 24
	s_add_i32 s16, s16, 28
	s_add_i32 s17, s17, 28
	v_add_u32_e32 v26, v13, v14
	v_or_b32_e32 v15, s18, v1
	v_or_b32_e32 v56, s19, v0
	v_or_b32_e32 v57, s20, v1
	v_or_b32_e32 v58, s21, v0
	v_or_b32_e32 v59, s22, v1
	v_or_b32_e32 v60, s23, v0
	v_or_b32_e32 v61, s24, v1
	v_or_b32_e32 v62, s25, v0
	v_or_b32_e32 v63, s26, v1
	v_or_b32_e32 v64, s27, v0
	v_or_b32_e32 v65, s28, v1
	v_or_b32_e32 v66, s29, v0
	v_or_b32_e32 v67, s16, v1
	v_or_b32_e32 v68, s17, v0
	v_add_u32_e32 v24, v7, v3
	v_ashrrev_i32_e32 v27, 31, v26
	v_add_u32_e32 v28, v15, v3
	v_add_u32_e32 v30, v56, v14
	v_add_u32_e32 v32, v57, v3
	v_add_u32_e32 v34, v58, v14
	v_add_u32_e32 v36, v59, v3
	v_add_u32_e32 v38, v60, v14
	v_add_u32_e32 v40, v61, v3
	v_add_u32_e32 v42, v62, v14
	v_add_u32_e32 v44, v63, v3
	v_add_u32_e32 v46, v64, v14
	v_add_u32_e32 v48, v65, v3
	v_add_u32_e32 v50, v66, v14
	v_add_u32_e32 v52, v67, v3
	v_add_u32_e32 v54, v68, v14
	v_ashrrev_i32_e32 v25, 31, v24
	v_lshlrev_b64 v[26:27], 13, v[26:27]
	v_ashrrev_i32_e32 v31, 31, v30
	v_ashrrev_i32_e32 v29, 31, v28
	v_ashrrev_i32_e32 v35, 31, v34
	v_ashrrev_i32_e32 v33, 31, v32
	v_ashrrev_i32_e32 v39, 31, v38
	v_ashrrev_i32_e32 v37, 31, v36
	v_ashrrev_i32_e32 v43, 31, v42
	v_ashrrev_i32_e32 v41, 31, v40
	v_ashrrev_i32_e32 v47, 31, v46
	v_ashrrev_i32_e32 v45, 31, v44
	v_ashrrev_i32_e32 v51, 31, v50
	v_ashrrev_i32_e32 v49, 31, v48
	v_ashrrev_i32_e32 v55, 31, v54
	v_ashrrev_i32_e32 v53, 31, v52
	v_lshlrev_b64 v[24:25], 13, v[24:25]
	v_lshl_add_u64 v[26:27], v[16:17], 0, v[26:27]
	v_lshlrev_b64 v[28:29], 13, v[28:29]
	v_lshlrev_b64 v[30:31], 13, v[30:31]
	v_lshlrev_b64 v[32:33], 13, v[32:33]
	v_lshlrev_b64 v[34:35], 13, v[34:35]
	v_lshlrev_b64 v[36:37], 13, v[36:37]
	v_lshlrev_b64 v[38:39], 13, v[38:39]
	v_lshlrev_b64 v[40:41], 13, v[40:41]
	v_lshlrev_b64 v[42:43], 13, v[42:43]
	v_lshlrev_b64 v[44:45], 13, v[44:45]
	v_lshlrev_b64 v[46:47], 13, v[46:47]
	v_lshlrev_b64 v[48:49], 13, v[48:49]
	v_lshlrev_b64 v[50:51], 13, v[50:51]
	v_lshlrev_b64 v[52:53], 13, v[52:53]
	v_lshlrev_b64 v[54:55], 13, v[54:55]
	v_lshl_add_u64 v[24:25], v[16:17], 0, v[24:25]
	v_lshl_add_u64 v[30:31], v[16:17], 0, v[30:31]
	v_lshl_add_u64 v[28:29], v[16:17], 0, v[28:29]
	v_lshl_add_u64 v[34:35], v[16:17], 0, v[34:35]
	v_lshl_add_u64 v[32:33], v[16:17], 0, v[32:33]
	v_lshl_add_u64 v[38:39], v[16:17], 0, v[38:39]
	v_lshl_add_u64 v[36:37], v[16:17], 0, v[36:37]
	v_lshl_add_u64 v[42:43], v[16:17], 0, v[42:43]
	v_lshl_add_u64 v[40:41], v[16:17], 0, v[40:41]
	v_lshl_add_u64 v[46:47], v[16:17], 0, v[46:47]
	v_lshl_add_u64 v[44:45], v[16:17], 0, v[44:45]
	v_lshl_add_u64 v[50:51], v[16:17], 0, v[50:51]
	v_lshl_add_u64 v[48:49], v[16:17], 0, v[48:49]
	v_lshl_add_u64 v[54:55], v[16:17], 0, v[54:55]
	v_lshl_add_u64 v[52:53], v[16:17], 0, v[52:53]
	global_load_dword v69, v[26:27], off nt
	global_load_dword v70, v[24:25], off nt
	global_load_dword v71, v[30:31], off nt
	global_load_dword v72, v[28:29], off nt
	global_load_dword v73, v[34:35], off nt
	global_load_dword v74, v[32:33], off nt
	global_load_dword v75, v[38:39], off nt
	global_load_dword v76, v[36:37], off nt
	global_load_dword v77, v[42:43], off nt
	global_load_dword v78, v[40:41], off nt
	global_load_dword v79, v[46:47], off nt
	global_load_dword v80, v[44:45], off nt
	global_load_dword v81, v[50:51], off nt
	global_load_dword v82, v[48:49], off nt
	global_load_dword v83, v[54:55], off nt
	global_load_dword v84, v[52:53], off nt
	s_add_i32 s14, s14, 16
	s_add_i32 s15, s15, 16
	s_add_i32 s9, s9, -16
	v_mad_u64_u32 v[24:25], s[16:17], v13, s11, v[2:3]
	s_cmp_lg_u32 s9, 0
	v_mad_u64_u32 v[26:27], s[16:17], v7, s11, v[2:3]
	v_mad_u64_u32 v[28:29], s[16:17], v56, s11, v[2:3]
	v_mad_u64_u32 v[30:31], s[16:17], v15, s11, v[2:3]
	v_mad_u64_u32 v[32:33], s[16:17], v58, s11, v[2:3]
	v_mad_u64_u32 v[34:35], s[16:17], v57, s11, v[2:3]
	v_mad_u64_u32 v[36:37], s[16:17], v60, s11, v[2:3]
	v_mad_u64_u32 v[38:39], s[16:17], v59, s11, v[2:3]
	v_mad_u64_u32 v[40:41], s[16:17], v62, s11, v[2:3]
	v_mad_u64_u32 v[42:43], s[16:17], v61, s11, v[2:3]
	v_mad_u64_u32 v[44:45], s[16:17], v64, s11, v[2:3]
	v_mad_u64_u32 v[46:47], s[16:17], v63, s11, v[2:3]
	v_mad_u64_u32 v[48:49], s[16:17], v66, s11, v[2:3]
	v_mad_u64_u32 v[50:51], s[16:17], v65, s11, v[2:3]
	v_mad_u64_u32 v[52:53], s[16:17], v68, s11, v[2:3]
	v_mad_u64_u32 v[54:55], s[16:17], v67, s11, v[2:3]
	s_waitcnt vmcnt(15)
	ds_write_b32 v24, v69
	s_waitcnt vmcnt(14)
	ds_write_b32 v26, v70
	s_waitcnt vmcnt(13)
	ds_write_b32 v28, v71
	s_waitcnt vmcnt(12)
	ds_write_b32 v30, v72
	s_waitcnt vmcnt(11)
	ds_write_b32 v32, v73
	s_waitcnt vmcnt(10)
	ds_write_b32 v34, v74
	s_waitcnt vmcnt(9)
	ds_write_b32 v36, v75
	s_waitcnt vmcnt(8)
	ds_write_b32 v38, v76
	s_waitcnt vmcnt(7)
	ds_write_b32 v40, v77
	s_waitcnt vmcnt(6)
	ds_write_b32 v42, v78
	s_waitcnt vmcnt(5)
	ds_write_b32 v44, v79
	s_waitcnt vmcnt(4)
	ds_write_b32 v46, v80
	s_waitcnt vmcnt(3)
	ds_write_b32 v48, v81
	s_waitcnt vmcnt(2)
	ds_write_b32 v50, v82
	s_waitcnt vmcnt(1)
	ds_write_b32 v52, v83
	s_waitcnt vmcnt(0)
	ds_write_b32 v54, v84
	s_cbranch_scc1 .LBB0_1211
; #define LAS __attribute__((address_space(3)))
;     __device__ __forceinline__ const float* in(int i) const { return (const float*)(const __attribute__((address_space(1))) float*)ld(i); }
; __device__ __forceinline__ unsigned pk2(float lo, float hi) { unsigned r; asm("v_cvt_pk_bf16_f32 %0, %1, %2" : "=v"(r) : "v"(lo), "v"(hi)); return r; }
; __device__ __forceinline__ void transpose_item(const float* W, int ldw, bf16_t* WT, int ldo, LAS float* scr, int k0, int n0, int lane, const float* rs = nullptr) {
;     ...
;     const int c = lane & 7;
; #pragma unroll
;     for (int j = 0; j < 4; ++j) { const int n = (lane >> 3) + 8 * j; const LAS float* s = scr + (8 * c) * 33 + n; const float m = rs ? rs[n0 + n] : 1.f;
;         u32x4 o; o.x = pk2(s[0 * 33] * m, s[1 * 33] * m); o.y = pk2(s[2 * 33] * m, s[3 * 33] * m); o.z = pk2(s[4 * 33] * m, s[5 * 33] * m); o.w = pk2(s[6 * 33] * m, s[7 * 33] * m);
;         *(u32x4*)(WT + (size_t)(n0 + n) * ldo + k0 + 8 * c) = o; }
;     asm volatile("s_waitcnt lgkmcnt(0)" ::: "memory");
; __device__ __forceinline__ void convert_sub(const DArgs& a, LAS unsigned char* lds, int which, int c0) {
;     ...
;     case CV_OUT1: transpose_matrix(a.in(I_WOUT1), D, D, (bf16_t*)(w + W_OUT1T), D, scr, gw, ngw, lane); break;
	s_waitcnt lgkmcnt(0)
	ds_read2_b32 v[28:29], v19 offset0:33 offset1:41
	ds_read2_b32 v[30:31], v19 offset1:8
	ds_read2_b32 v[32:33], v19 offset0:66 offset1:74
	ds_read2_b32 v[34:35], v19 offset0:99 offset1:107
	ds_read2_b32 v[36:37], v19 offset0:132 offset1:140
	ds_read2_b32 v[38:39], v19 offset0:165 offset1:173
	ds_read2_b32 v[40:41], v19 offset0:198 offset1:206
	ds_read2_b32 v[42:43], v19 offset0:231 offset1:239
	v_or_b32_e32 v26, v12, v18
	v_ashrrev_i32_e32 v15, 31, v14
	v_ashrrev_i32_e32 v27, 31, v26
	v_lshl_add_u64 v[24:25], v[14:15], 1, v[10:11]
	v_lshlrev_b64 v[26:27], 12, v[26:27]
	v_lshl_add_u64 v[26:27], v[24:25], 0, v[26:27]
	s_waitcnt lgkmcnt(6)
	v_cvt_pk_bf16_f32 v14, v30, v28
	s_waitcnt lgkmcnt(4)
	v_cvt_pk_bf16_f32 v15, v32, v34
	s_waitcnt lgkmcnt(2)
	v_cvt_pk_bf16_f32 v16, v36, v38
	s_waitcnt lgkmcnt(0)
	v_cvt_pk_bf16_f32 v17, v40, v42
	global_store_dwordx4 v[26:27], v[14:17], off
	v_or_b32_e32 v26, v12, v20
	v_ashrrev_i32_e32 v27, 31, v26
	v_lshlrev_b64 v[26:27], 12, v[26:27]
	v_lshl_add_u64 v[26:27], v[24:25], 0, v[26:27]
	v_cvt_pk_bf16_f32 v14, v31, v29
	v_cvt_pk_bf16_f32 v15, v33, v35
	v_cvt_pk_bf16_f32 v16, v37, v39
	v_cvt_pk_bf16_f32 v17, v41, v43
	global_store_dwordx4 v[26:27], v[14:17], off
	ds_read2_b32 v[28:29], v19 offset0:16 offset1:24
	ds_read2_b32 v[30:31], v19 offset0:49 offset1:57
	ds_read2_b32 v[32:33], v19 offset0:82 offset1:90
	ds_read2_b32 v[34:35], v19 offset0:115 offset1:123
	ds_read2_b32 v[36:37], v19 offset0:148 offset1:156
	ds_read2_b32 v[38:39], v19 offset0:181 offset1:189
	ds_read2_b32 v[40:41], v19 offset0:214 offset1:222
	ds_read2_b32 v[42:43], v19 offset0:247 offset1:255
	v_or_b32_e32 v26, v12, v21
	v_ashrrev_i32_e32 v27, 31, v26
	v_lshlrev_b64 v[26:27], 12, v[26:27]
	s_waitcnt lgkmcnt(2)
	v_cvt_pk_bf16_f32 v16, v36, v38
	v_lshl_add_u64 v[26:27], v[24:25], 0, v[26:27]
	v_cvt_pk_bf16_f32 v14, v28, v30
	v_cvt_pk_bf16_f32 v15, v32, v34
	s_waitcnt lgkmcnt(0)
	v_cvt_pk_bf16_f32 v17, v40, v42
	global_store_dwordx4 v[26:27], v[14:17], off
	v_cvt_pk_bf16_f32 v13, v33, v35
	v_add_u32_e32 v5, s10, v5
	v_cmp_lt_i32_e32 vcc, s8, v5
	v_or_b32_e32 v16, v12, v22
	v_ashrrev_i32_e32 v17, 31, v16
	v_lshlrev_b64 v[16:17], 12, v[16:17]
	v_lshl_add_u64 v[16:17], v[24:25], 0, v[16:17]
	v_cvt_pk_bf16_f32 v12, v29, v31
	v_cvt_pk_bf16_f32 v14, v37, v39
	v_cvt_pk_bf16_f32 v15, v41, v43
	global_store_dwordx4 v[16:17], v[12:15], off
	s_waitcnt lgkmcnt(0)
	s_or_b64 s[6:7], vcc, s[6:7]
	s_andn2_b64 exec, exec, s[6:7]
	s_cbranch_execnz .LBB0_1210
	s_or_b64 exec, exec, s[6:7]
	s_add_i32 s6, 0, 0x20108
	v_mov_b32_e32 v1, s6
	ds_read_b64 v[8:9], v1

; #define LAS __attribute__((address_space(3)))
;     __device__ __forceinline__ const float* in(int i) const { return (const float*)(const __attribute__((address_space(1))) float*)ld(i); }
; __device__ __forceinline__ void transpose_item(const float* W, int ldw, bf16_t* WT, int ldo, LAS float* scr, int k0, int n0, int lane, const float* rs = nullptr) {
; #pragma unroll 8
;     for (int i = 0; i < 32; ++i) { const int kk = 2 * i + (lane >> 5); scr[kk * 33 + (lane & 31)] = W[(size_t)(k0 + kk) * ldw + n0 + (lane & 31)]; }
;     asm volatile("s_waitcnt lgkmcnt(0)" ::: "memory");
; __device__ __forceinline__ void phase_attn_prep(const DArgs& a, LAS unsigned char* lds) {
;     ...
;     for (int it = gw; it < 8 * 512; it += ngw) { const int b = it >> 9, r = it & 511, kb = r >> 6, nb = r & 63;
;         transpose_item(a.in(I_CV) + (size_t)b * 512 * D, D, VsT + (size_t)b * D * 576, 576, scr, kb * 64, nb * 32, lane); }
.LBB0_1287:
	s_lshl_b32 s23, s22, 1
	s_lshl_b32 s24, s21, 1
	v_or_b32_e32 v45, s24, v0
	s_add_i32 s25, s23, 4
	s_add_i32 s26, s24, 4
	s_add_i32 s28, s24, 8
	v_add_u32_e32 v2, v45, v10
	v_or_b32_e32 v46, s25, v1
	v_or_b32_e32 v47, s26, v0
	v_mov_b32_e32 v25, v3
	v_or_b32_e32 v44, s23, v1
	s_add_i32 s30, s24, 12
	v_or_b32_e32 v49, s28, v0
	v_lshlrev_b64 v[38:39], 13, v[2:3]
	v_add_u32_e32 v24, v46, v5
	v_add_u32_e32 v2, v47, v10
	v_mov_b32_e32 v23, v3
	s_add_i32 s27, s23, 8
	s_add_i32 s29, s23, 12
	s_add_i32 s33, s24, 16
	v_add_u32_e32 v22, v44, v5
	v_or_b32_e32 v51, s30, v0
	v_lshlrev_b64 v[24:25], 13, v[24:25]
	v_lshlrev_b64 v[40:41], 13, v[2:3]
	v_add_u32_e32 v2, v49, v10
	s_add_i32 s35, s24, 20
	v_or_b32_e32 v48, s27, v1
	v_or_b32_e32 v50, s29, v1
	v_or_b32_e32 v53, s33, v0
	v_lshlrev_b64 v[22:23], 13, v[22:23]
	v_lshl_add_u64 v[38:39], v[14:15], 0, v[38:39]
	v_lshl_add_u64 v[24:25], v[14:15], 0, v[24:25]
	v_lshlrev_b64 v[42:43], 13, v[2:3]
	v_add_u32_e32 v2, v51, v10
	v_mov_b32_e32 v27, v3
	v_mov_b32_e32 v29, v3
	s_add_i32 s31, s23, 16
	s_add_i32 s34, s23, 20
	s_add_i32 s37, s24, 24
	v_or_b32_e32 v55, s35, v0
	v_add_u32_e32 v26, v48, v5
	v_add_u32_e32 v28, v50, v5
	v_lshl_add_u64 v[22:23], v[14:15], 0, v[22:23]
	v_lshl_add_u64 v[40:41], v[14:15], 0, v[40:41]
	global_load_dword v60, v[38:39], off nt
	global_load_dword v61, v[22:23], off nt
	global_load_dword v62, v[40:41], off nt
	global_load_dword v63, v[24:25], off nt
	v_lshlrev_b64 v[24:25], 13, v[2:3]
	v_add_u32_e32 v2, v53, v10
	s_add_i32 s36, s23, 24
	s_add_i32 s23, s23, 28
	s_add_i32 s24, s24, 28
	v_or_b32_e32 v52, s31, v1
	v_or_b32_e32 v54, s34, v1
	v_or_b32_e32 v57, s37, v0
	v_lshlrev_b64 v[26:27], 13, v[26:27]
	v_lshlrev_b64 v[28:29], 13, v[28:29]
	v_lshl_add_u64 v[22:23], v[14:15], 0, v[42:43]
	v_lshl_add_u64 v[24:25], v[14:15], 0, v[24:25]
	v_lshlrev_b64 v[38:39], 13, v[2:3]
	v_add_u32_e32 v2, v55, v10
	v_mov_b32_e32 v31, v3
	v_mov_b32_e32 v33, v3
	v_or_b32_e32 v56, s36, v1
	v_or_b32_e32 v58, s23, v1
	v_or_b32_e32 v59, s24, v0
	v_add_u32_e32 v30, v52, v5
	v_add_u32_e32 v32, v54, v5
	v_lshl_add_u64 v[26:27], v[14:15], 0, v[26:27]
	v_lshl_add_u64 v[28:29], v[14:15], 0, v[28:29]
	global_load_dword v64, v[22:23], off nt
	global_load_dword v65, v[26:27], off nt
	global_load_dword v66, v[24:25], off nt
	global_load_dword v67, v[28:29], off nt
	v_lshlrev_b64 v[24:25], 13, v[2:3]
	v_add_u32_e32 v2, v57, v10
	v_mov_b32_e32 v35, v3
	v_mov_b32_e32 v37, v3
	v_add_u32_e32 v34, v56, v5
	v_add_u32_e32 v36, v58, v5
	v_lshlrev_b64 v[30:31], 13, v[30:31]
	v_lshlrev_b64 v[32:33], 13, v[32:33]
	v_lshl_add_u64 v[22:23], v[14:15], 0, v[38:39]
	v_lshl_add_u64 v[24:25], v[14:15], 0, v[24:25]
	v_lshlrev_b64 v[26:27], 13, v[2:3]
	v_add_u32_e32 v2, v59, v10
	v_lshlrev_b64 v[34:35], 13, v[34:35]
	v_lshlrev_b64 v[36:37], 13, v[36:37]
	v_lshl_add_u64 v[30:31], v[14:15], 0, v[30:31]
	v_lshl_add_u64 v[32:33], v[14:15], 0, v[32:33]
	global_load_dword v68, v[22:23], off nt
	global_load_dword v69, v[30:31], off nt
	global_load_dword v70, v[24:25], off nt
	global_load_dword v71, v[32:33], off nt
	v_lshl_add_u64 v[22:23], v[14:15], 0, v[26:27]
	v_lshlrev_b64 v[24:25], 13, v[2:3]
	v_lshl_add_u64 v[34:35], v[14:15], 0, v[34:35]
	v_lshl_add_u64 v[36:37], v[14:15], 0, v[36:37]
	v_lshl_add_u64 v[24:25], v[14:15], 0, v[24:25]
	global_load_dword v2, v[22:23], off nt
	global_load_dword v72, v[34:35], off nt
	global_load_dword v73, v[24:25], off nt
	global_load_dword v74, v[36:37], off nt
	s_add_i32 s21, s21, 16
	s_add_i32 s22, s22, 16
	s_add_i32 s20, s20, -16
	v_mad_u64_u32 v[22:23], s[24:25], v45, s18, v[4:5]
	s_cmp_lg_u32 s20, 0
	v_mad_u64_u32 v[24:25], s[24:25], v44, s18, v[4:5]
	v_mad_u64_u32 v[26:27], s[24:25], v47, s18, v[4:5]
	v_mad_u64_u32 v[28:29], s[24:25], v46, s18, v[4:5]
	v_mad_u64_u32 v[30:31], s[24:25], v49, s18, v[4:5]
	v_mad_u64_u32 v[32:33], s[24:25], v48, s18, v[4:5]
	v_mad_u64_u32 v[34:35], s[24:25], v51, s18, v[4:5]
	v_mad_u64_u32 v[36:37], s[24:25], v50, s18, v[4:5]
	v_mad_u64_u32 v[38:39], s[24:25], v53, s18, v[4:5]
	v_mad_u64_u32 v[40:41], s[24:25], v52, s18, v[4:5]
	v_mad_u64_u32 v[42:43], s[24:25], v55, s18, v[4:5]
	v_mad_u64_u32 v[44:45], s[24:25], v54, s18, v[4:5]
	v_mad_u64_u32 v[46:47], s[24:25], v57, s18, v[4:5]
	v_mad_u64_u32 v[48:49], s[24:25], v56, s18, v[4:5]
	v_mad_u64_u32 v[50:51], s[24:25], v59, s18, v[4:5]
	v_mad_u64_u32 v[52:53], s[24:25], v58, s18, v[4:5]
	s_waitcnt vmcnt(15)
	ds_write_b32 v22, v60
	s_waitcnt vmcnt(14)
	ds_write_b32 v24, v61
	s_waitcnt vmcnt(13)
	ds_write_b32 v26, v62
	s_waitcnt vmcnt(12)
	ds_write_b32 v28, v63
	s_waitcnt vmcnt(11)
	ds_write_b32 v30, v64
	s_waitcnt vmcnt(10)
	ds_write_b32 v32, v65
	s_waitcnt vmcnt(9)
	ds_write_b32 v34, v66
	s_waitcnt vmcnt(8)
	ds_write_b32 v36, v67
	s_waitcnt vmcnt(7)
	ds_write_b32 v38, v68
	s_waitcnt vmcnt(6)
	ds_write_b32 v40, v69
	s_waitcnt vmcnt(5)
	ds_write_b32 v42, v70
	s_waitcnt vmcnt(4)
	ds_write_b32 v44, v71
	s_waitcnt vmcnt(3)
	ds_write_b32 v46, v2
	s_waitcnt vmcnt(2)
	ds_write_b32 v48, v72
	s_waitcnt vmcnt(1)
	ds_write_b32 v50, v73
	s_waitcnt vmcnt(0)
	ds_write_b32 v52, v74
	s_cbranch_scc1 .LBB0_1287
; #define LAS __attribute__((address_space(3)))
;     __device__ __forceinline__ const float* in(int i) const { return (const float*)(const __attribute__((address_space(1))) float*)ld(i); }
; __device__ __forceinline__ unsigned pk2(float lo, float hi) { unsigned r; asm("v_cvt_pk_bf16_f32 %0, %1, %2" : "=v"(r) : "v"(lo), "v"(hi)); return r; }
; __device__ __forceinline__ void transpose_item(const float* W, int ldw, bf16_t* WT, int ldo, LAS float* scr, int k0, int n0, int lane, const float* rs = nullptr) {
;     ...
;     const int c = lane & 7;
; #pragma unroll
;     for (int j = 0; j < 4; ++j) { const int n = (lane >> 3) + 8 * j; const LAS float* s = scr + (8 * c) * 33 + n; const float m = rs ? rs[n0 + n] : 1.f;
;         u32x4 o; o.x = pk2(s[0 * 33] * m, s[1 * 33] * m); o.y = pk2(s[2 * 33] * m, s[3 * 33] * m); o.z = pk2(s[4 * 33] * m, s[5 * 33] * m); o.w = pk2(s[6 * 33] * m, s[7 * 33] * m);
;         *(u32x4*)(WT + (size_t)(n0 + n) * ldo + k0 + 8 * c) = o; }
;     asm volatile("s_waitcnt lgkmcnt(0)" ::: "memory");
; __device__ __forceinline__ void phase_attn_prep(const DArgs& a, LAS unsigned char* lds) {
;     ...
;     for (int it = gw; it < 8 * 512; it += ngw) { const int b = it >> 9, r = it & 511, kb = r >> 6, nb = r & 63;
;         transpose_item(a.in(I_CV) + (size_t)b * 512 * D, D, VsT + (size_t)b * D * 576, 576, scr, kb * 64, nb * 32, lane); }
	v_mul_hi_i32_i24_e32 v15, 0x240000, v12
	v_mul_i32_i24_e32 v14, 0x240000, v12
	v_lshl_add_u64 v[14:15], s[10:11], 0, v[14:15]
	v_lshlrev_b32_e32 v2, 1, v10
	s_waitcnt lgkmcnt(0)
	v_lshl_add_u64 v[14:15], v[14:15], 0, v[2:3]
	v_or_b32_e32 v2, v13, v16
	v_lshl_add_u64 v[26:27], v[14:15], 0, v[8:9]
	ds_read2_b32 v[14:15], v17 offset0:33 offset1:41
	ds_read2_b32 v[28:29], v17 offset1:8
	ds_read2_b32 v[30:31], v17 offset0:66 offset1:74
	ds_read2_b32 v[32:33], v17 offset0:99 offset1:107
	ds_read2_b32 v[34:35], v17 offset0:132 offset1:140
	ds_read2_b32 v[36:37], v17 offset0:165 offset1:173
	ds_read2_b32 v[38:39], v17 offset0:198 offset1:206
	ds_read2_b32 v[40:41], v17 offset0:231 offset1:239
	v_mul_u32_u24_e32 v2, 0x240, v2
	v_lshlrev_b32_e32 v2, 1, v2
	v_lshl_add_u64 v[42:43], v[26:27], 0, v[2:3]
	v_or_b32_e32 v2, v13, v18
	v_mul_u32_u24_e32 v2, 0x240, v2
	s_waitcnt lgkmcnt(6)
	v_cvt_pk_bf16_f32 v22, v28, v14
	v_lshlrev_b32_e32 v2, 1, v2
	s_waitcnt lgkmcnt(4)
	v_cvt_pk_bf16_f32 v23, v30, v32
	s_waitcnt lgkmcnt(2)
	v_cvt_pk_bf16_f32 v24, v34, v36
	s_waitcnt lgkmcnt(0)
	v_cvt_pk_bf16_f32 v25, v38, v40
	global_store_dwordx4 v[42:43], v[22:25], off
	v_add_u32_e32 v11, s7, v11
	v_cmp_lt_i32_e32 vcc, s19, v11
	v_cvt_pk_bf16_f32 v22, v29, v15
	v_lshl_add_u64 v[14:15], v[26:27], 0, v[2:3]
	v_cvt_pk_bf16_f32 v23, v31, v33
	v_cvt_pk_bf16_f32 v24, v35, v37
	v_cvt_pk_bf16_f32 v25, v39, v41
	global_store_dwordx4 v[14:15], v[22:25], off
	v_or_b32_e32 v2, v13, v19
	ds_read2_b32 v[14:15], v17 offset0:16 offset1:24
	ds_read2_b32 v[28:29], v17 offset0:49 offset1:57
	ds_read2_b32 v[30:31], v17 offset0:82 offset1:90
	ds_read2_b32 v[32:33], v17 offset0:115 offset1:123
	ds_read2_b32 v[34:35], v17 offset0:148 offset1:156
	ds_read2_b32 v[36:37], v17 offset0:181 offset1:189
	ds_read2_b32 v[38:39], v17 offset0:214 offset1:222
	ds_read2_b32 v[40:41], v17 offset0:247 offset1:255
	v_mul_u32_u24_e32 v2, 0x240, v2
	v_lshlrev_b32_e32 v2, 1, v2
	v_lshl_add_u64 v[42:43], v[26:27], 0, v[2:3]
	v_or_b32_e32 v2, v13, v20
	v_mul_u32_u24_e32 v2, 0x240, v2
	s_waitcnt lgkmcnt(6)
	v_cvt_pk_bf16_f32 v22, v14, v28
	s_waitcnt lgkmcnt(4)
	v_cvt_pk_bf16_f32 v23, v30, v32
	v_lshlrev_b32_e32 v2, 1, v2
	s_waitcnt lgkmcnt(2)
	v_cvt_pk_bf16_f32 v24, v34, v36
	s_waitcnt lgkmcnt(0)
	v_cvt_pk_bf16_f32 v25, v38, v40
	global_store_dwordx4 v[42:43], v[22:25], off
	v_cvt_pk_bf16_f32 v12, v15, v29
	v_cvt_pk_bf16_f32 v13, v31, v33
	v_cvt_pk_bf16_f32 v14, v35, v37
	v_cvt_pk_bf16_f32 v15, v39, v41
	s_or_b64 s[16:17], vcc, s[16:17]
	s_nop 0
	v_lshl_add_u64 v[22:23], v[26:27], 0, v[2:3]
	global_store_dwordx4 v[22:23], v[12:15], off
	s_waitcnt lgkmcnt(0)
	s_andn2_b64 exec, exec, s[16:17]
	s_cbranch_execnz .LBB0_1286

; #define LAS __attribute__((address_space(3)))
; __device__ __forceinline__ void transpose_item(const float* W, int ldw, bf16_t* WT, int ldo, LAS float* scr, int k0, int n0, int lane, const float* rs = nullptr) {
; #pragma unroll 8
;     for (int i = 0; i < 32; ++i) { const int kk = 2 * i + (lane >> 5); scr[kk * 33 + (lane & 31)] = W[(size_t)(k0 + kk) * ldw + n0 + (lane & 31)]; }
.LBB0_1626:
	s_lshl_b32 s16, s15, 1
	s_lshl_b32 s17, s9, 1
	v_or_b32_e32 v9, s16, v1
	v_or_b32_e32 v11, s17, v0
	s_add_i32 s18, s16, 4
	s_add_i32 s19, s17, 4
	s_add_i32 s20, s16, 8
	s_add_i32 s21, s17, 8
	s_add_i32 s22, s16, 12
	s_add_i32 s23, s17, 12
	s_add_i32 s24, s16, 16
	s_add_i32 s25, s17, 16
	s_add_i32 s26, s16, 20
	s_add_i32 s27, s17, 20
	s_add_i32 s28, s16, 24
	s_add_i32 s29, s17, 24
	s_add_i32 s16, s16, 28
	s_add_i32 s17, s17, 28
	v_add_u32_e32 v22, v11, v10
	v_or_b32_e32 v52, s18, v1
	v_or_b32_e32 v53, s19, v0
	v_or_b32_e32 v54, s20, v1
	v_or_b32_e32 v55, s21, v0
	v_or_b32_e32 v56, s22, v1
	v_or_b32_e32 v57, s23, v0
	v_or_b32_e32 v58, s24, v1
	v_or_b32_e32 v59, s25, v0
	v_or_b32_e32 v60, s26, v1
	v_or_b32_e32 v61, s27, v0
	v_or_b32_e32 v62, s28, v1
	v_or_b32_e32 v63, s29, v0
	v_or_b32_e32 v64, s16, v1
	v_or_b32_e32 v65, s17, v0
	v_add_u32_e32 v20, v9, v3
	v_ashrrev_i32_e32 v23, 31, v22
	v_add_u32_e32 v24, v52, v3
	v_add_u32_e32 v26, v53, v10
	v_add_u32_e32 v28, v54, v3
	v_add_u32_e32 v30, v55, v10
	v_add_u32_e32 v32, v56, v3
	v_add_u32_e32 v34, v57, v10
	v_add_u32_e32 v36, v58, v3
	v_add_u32_e32 v38, v59, v10
	v_add_u32_e32 v40, v60, v3
	v_add_u32_e32 v42, v61, v10
	v_add_u32_e32 v44, v62, v3
	v_add_u32_e32 v46, v63, v10
	v_add_u32_e32 v48, v64, v3
	v_add_u32_e32 v50, v65, v10
	v_ashrrev_i32_e32 v21, 31, v20
	v_lshlrev_b64 v[22:23], 13, v[22:23]
	v_ashrrev_i32_e32 v27, 31, v26
	v_ashrrev_i32_e32 v25, 31, v24
	v_ashrrev_i32_e32 v31, 31, v30
	v_ashrrev_i32_e32 v29, 31, v28
	v_ashrrev_i32_e32 v35, 31, v34
	v_ashrrev_i32_e32 v33, 31, v32
	v_ashrrev_i32_e32 v39, 31, v38
	v_ashrrev_i32_e32 v37, 31, v36
	v_ashrrev_i32_e32 v43, 31, v42
	v_ashrrev_i32_e32 v41, 31, v40
	v_ashrrev_i32_e32 v47, 31, v46
	v_ashrrev_i32_e32 v45, 31, v44
	v_ashrrev_i32_e32 v51, 31, v50
	v_ashrrev_i32_e32 v49, 31, v48
	v_lshlrev_b64 v[20:21], 13, v[20:21]
	v_lshl_add_u64 v[22:23], v[12:13], 0, v[22:23]
	v_lshlrev_b64 v[24:25], 13, v[24:25]
	v_lshlrev_b64 v[26:27], 13, v[26:27]
	v_lshlrev_b64 v[28:29], 13, v[28:29]
	v_lshlrev_b64 v[30:31], 13, v[30:31]
	v_lshlrev_b64 v[32:33], 13, v[32:33]
	v_lshlrev_b64 v[34:35], 13, v[34:35]
	v_lshlrev_b64 v[36:37], 13, v[36:37]
	v_lshlrev_b64 v[38:39], 13, v[38:39]
	v_lshlrev_b64 v[40:41], 13, v[40:41]
	v_lshlrev_b64 v[42:43], 13, v[42:43]
	v_lshlrev_b64 v[44:45], 13, v[44:45]
	v_lshlrev_b64 v[46:47], 13, v[46:47]
	v_lshlrev_b64 v[48:49], 13, v[48:49]
	v_lshlrev_b64 v[50:51], 13, v[50:51]
	v_lshl_add_u64 v[20:21], v[12:13], 0, v[20:21]
	v_lshl_add_u64 v[26:27], v[12:13], 0, v[26:27]
	v_lshl_add_u64 v[24:25], v[12:13], 0, v[24:25]
	v_lshl_add_u64 v[30:31], v[12:13], 0, v[30:31]
	v_lshl_add_u64 v[28:29], v[12:13], 0, v[28:29]
	v_lshl_add_u64 v[34:35], v[12:13], 0, v[34:35]
	v_lshl_add_u64 v[32:33], v[12:13], 0, v[32:33]
	v_lshl_add_u64 v[38:39], v[12:13], 0, v[38:39]
	v_lshl_add_u64 v[36:37], v[12:13], 0, v[36:37]
	v_lshl_add_u64 v[42:43], v[12:13], 0, v[42:43]
	v_lshl_add_u64 v[40:41], v[12:13], 0, v[40:41]
	v_lshl_add_u64 v[46:47], v[12:13], 0, v[46:47]
	v_lshl_add_u64 v[44:45], v[12:13], 0, v[44:45]
	v_lshl_add_u64 v[50:51], v[12:13], 0, v[50:51]
	v_lshl_add_u64 v[48:49], v[12:13], 0, v[48:49]
	global_load_dword v66, v[22:23], off nt
	global_load_dword v67, v[20:21], off nt
	global_load_dword v68, v[26:27], off nt
	global_load_dword v69, v[24:25], off nt
	global_load_dword v70, v[30:31], off nt
	global_load_dword v71, v[28:29], off nt
	global_load_dword v72, v[34:35], off nt
	global_load_dword v73, v[32:33], off nt
	global_load_dword v74, v[38:39], off nt
	global_load_dword v75, v[36:37], off nt
	global_load_dword v76, v[42:43], off nt
	global_load_dword v77, v[40:41], off nt
	global_load_dword v78, v[46:47], off nt
	global_load_dword v79, v[44:45], off nt
	global_load_dword v80, v[50:51], off nt
	global_load_dword v81, v[48:49], off nt
	s_add_i32 s9, s9, 16
	s_add_i32 s15, s15, 16
	s_add_i32 s14, s14, -16
	v_mad_u64_u32 v[20:21], s[16:17], v11, s11, v[2:3]
	s_cmp_lg_u32 s14, 0
	v_mad_u64_u32 v[22:23], s[16:17], v9, s11, v[2:3]
	v_mad_u64_u32 v[24:25], s[16:17], v53, s11, v[2:3]
	v_mad_u64_u32 v[26:27], s[16:17], v52, s11, v[2:3]
	v_mad_u64_u32 v[28:29], s[16:17], v55, s11, v[2:3]
	v_mad_u64_u32 v[30:31], s[16:17], v54, s11, v[2:3]
	v_mad_u64_u32 v[32:33], s[16:17], v57, s11, v[2:3]
	v_mad_u64_u32 v[34:35], s[16:17], v56, s11, v[2:3]
	v_mad_u64_u32 v[36:37], s[16:17], v59, s11, v[2:3]
	v_mad_u64_u32 v[38:39], s[16:17], v58, s11, v[2:3]
	v_mad_u64_u32 v[40:41], s[16:17], v61, s11, v[2:3]
	v_mad_u64_u32 v[42:43], s[16:17], v60, s11, v[2:3]
	v_mad_u64_u32 v[44:45], s[16:17], v63, s11, v[2:3]
	v_mad_u64_u32 v[46:47], s[16:17], v62, s11, v[2:3]
	v_mad_u64_u32 v[48:49], s[16:17], v65, s11, v[2:3]
	v_mad_u64_u32 v[50:51], s[16:17], v64, s11, v[2:3]
	s_waitcnt vmcnt(15)
	ds_write_b32 v20, v66
	s_waitcnt vmcnt(14)
	ds_write_b32 v22, v67
	s_waitcnt vmcnt(13)
	ds_write_b32 v24, v68
	s_waitcnt vmcnt(12)
	ds_write_b32 v26, v69
	s_waitcnt vmcnt(11)
	ds_write_b32 v28, v70
	s_waitcnt vmcnt(10)
	ds_write_b32 v30, v71
	s_waitcnt vmcnt(9)
	ds_write_b32 v32, v72
	s_waitcnt vmcnt(8)
	ds_write_b32 v34, v73
	s_waitcnt vmcnt(7)
	ds_write_b32 v36, v74
	s_waitcnt vmcnt(6)
	ds_write_b32 v38, v75
	s_waitcnt vmcnt(5)
	ds_write_b32 v40, v76
	s_waitcnt vmcnt(4)
	ds_write_b32 v42, v77
	s_waitcnt vmcnt(3)
	ds_write_b32 v44, v78
	s_waitcnt vmcnt(2)
	ds_write_b32 v46, v79
	s_waitcnt vmcnt(1)
	ds_write_b32 v48, v80
	s_waitcnt vmcnt(0)
	ds_write_b32 v50, v81
	s_cbranch_scc1 .LBB0_1626
; #define LAS __attribute__((address_space(3)))
; __device__ __forceinline__ unsigned pk2(float lo, float hi) { unsigned r; asm("v_cvt_pk_bf16_f32 %0, %1, %2" : "=v"(r) : "v"(lo), "v"(hi)); return r; }
; __device__ __forceinline__ void transpose_item(const float* W, int ldw, bf16_t* WT, int ldo, LAS float* scr, int k0, int n0, int lane, const float* rs = nullptr) {
;     ...
;     asm volatile("s_waitcnt lgkmcnt(0)" ::: "memory");
;     const int c = lane & 7;
; #pragma unroll
;     for (int j = 0; j < 4; ++j) { const int n = (lane >> 3) + 8 * j; const LAS float* s = scr + (8 * c) * 33 + n; const float m = rs ? rs[n0 + n] : 1.f;
;         u32x4 o; o.x = pk2(s[0 * 33] * m, s[1 * 33] * m); o.y = pk2(s[2 * 33] * m, s[3 * 33] * m); o.z = pk2(s[4 * 33] * m, s[5 * 33] * m); o.w = pk2(s[6 * 33] * m, s[7 * 33] * m);
;         *(u32x4*)(WT + (size_t)(n0 + n) * ldo + k0 + 8 * c) = o; }
;     asm volatile("s_waitcnt lgkmcnt(0)" ::: "memory");
; }
; __device__ __forceinline__ void transpose_matrix(const float* W, int K, int N, bf16_t* WT, int ldo, LAS float* scr, int gw, int ngw, int lane, const float* rs = nullptr) {
;     const int nblk = N / 32, nitems = (K / 64) * nblk;
;     for (int it = gw; it < nitems; it += ngw) { const int kb = it / nblk, nb = it % nblk; transpose_item(W, N, WT, ldo, scr, kb * 64, nb * 32, lane, rs); }
	s_waitcnt lgkmcnt(0)
	ds_read2_b32 v[24:25], v16 offset0:33 offset1:41
	ds_read2_b32 v[26:27], v16 offset1:8
	ds_read2_b32 v[28:29], v16 offset0:66 offset1:74
	ds_read2_b32 v[30:31], v16 offset0:99 offset1:107
	ds_read2_b32 v[32:33], v16 offset0:132 offset1:140
	ds_read2_b32 v[34:35], v16 offset0:165 offset1:173
	ds_read2_b32 v[36:37], v16 offset0:198 offset1:206
	ds_read2_b32 v[38:39], v16 offset0:231 offset1:239
	v_or_b32_e32 v22, v8, v15
	v_ashrrev_i32_e32 v11, 31, v10
	v_ashrrev_i32_e32 v23, 31, v22
	v_lshl_add_u64 v[20:21], v[10:11], 1, v[6:7]
	v_lshlrev_b64 v[22:23], 14, v[22:23]
	v_lshl_add_u64 v[22:23], v[20:21], 0, v[22:23]
	s_waitcnt lgkmcnt(6)
	v_cvt_pk_bf16_f32 v10, v26, v24
	s_waitcnt lgkmcnt(4)
	v_cvt_pk_bf16_f32 v11, v28, v30
	s_waitcnt lgkmcnt(2)
	v_cvt_pk_bf16_f32 v12, v32, v34
	s_waitcnt lgkmcnt(0)
	v_cvt_pk_bf16_f32 v13, v36, v38
	global_store_dwordx4 v[22:23], v[10:13], off
	v_or_b32_e32 v22, v8, v17
	v_ashrrev_i32_e32 v23, 31, v22
	v_lshlrev_b64 v[22:23], 14, v[22:23]
	v_lshl_add_u64 v[22:23], v[20:21], 0, v[22:23]
	v_cvt_pk_bf16_f32 v10, v27, v25
	v_cvt_pk_bf16_f32 v11, v29, v31
	v_cvt_pk_bf16_f32 v12, v33, v35
	v_cvt_pk_bf16_f32 v13, v37, v39
	global_store_dwordx4 v[22:23], v[10:13], off
	ds_read2_b32 v[24:25], v16 offset0:16 offset1:24
	ds_read2_b32 v[26:27], v16 offset0:49 offset1:57
	ds_read2_b32 v[28:29], v16 offset0:82 offset1:90
	ds_read2_b32 v[30:31], v16 offset0:115 offset1:123
	ds_read2_b32 v[32:33], v16 offset0:148 offset1:156
	ds_read2_b32 v[34:35], v16 offset0:181 offset1:189
	ds_read2_b32 v[36:37], v16 offset0:214 offset1:222
	ds_read2_b32 v[38:39], v16 offset0:247 offset1:255
	v_or_b32_e32 v22, v8, v18
	v_ashrrev_i32_e32 v23, 31, v22
	v_lshlrev_b64 v[22:23], 14, v[22:23]
	s_waitcnt lgkmcnt(2)
	v_cvt_pk_bf16_f32 v12, v32, v34
	v_lshl_add_u64 v[22:23], v[20:21], 0, v[22:23]
	v_cvt_pk_bf16_f32 v10, v24, v26
	v_cvt_pk_bf16_f32 v11, v28, v30
	s_waitcnt lgkmcnt(0)
	v_cvt_pk_bf16_f32 v13, v36, v38
	global_store_dwordx4 v[22:23], v[10:13], off
	v_cvt_pk_bf16_f32 v9, v29, v31
	v_add_u32_e32 v14, s10, v14
	v_cmp_lt_i32_e32 vcc, s8, v14
	v_or_b32_e32 v12, v8, v19
	v_ashrrev_i32_e32 v13, 31, v12
	v_lshlrev_b64 v[12:13], 14, v[12:13]
	v_lshl_add_u64 v[12:13], v[20:21], 0, v[12:13]
	v_cvt_pk_bf16_f32 v8, v25, v27
	v_cvt_pk_bf16_f32 v10, v33, v35
	v_cvt_pk_bf16_f32 v11, v37, v39
	global_store_dwordx4 v[12:13], v[8:11], off
	s_waitcnt lgkmcnt(0)
	s_or_b64 s[6:7], vcc, s[6:7]
	s_andn2_b64 exec, exec, s[6:7]
	s_cbranch_execnz .LBB0_1625
